# E24: E23 + the redundant inner s_setprio 0/1 pair of each MFMA segment removed (segment runs at one priority between its barriers)
# baseline (speedup 1.0000x reference)
; #define PG8_STAGE(bufoff, gbase, voff) do { _Pragma("unroll") for (int _i = 0; _i < 2; ++_i) \
;         __builtin_amdgcn_global_load_lds((const unsigned*)((const char*)(gbase) + (voff)[_i]), (LAS unsigned*)(lds + (bufoff) + ldsw + _i * 8192), 16, 0, 0); } while (0)
; #define PG8_LDA(dst, b, h) do { _Pragma("unroll") for (int m = 0; m < 4; ++m) _Pragma("unroll") for (int k = 0; k < 2; ++k) dst[m][k] = *(const LAS bf16x8*)(lds + PG8_SA(b, h) + aoff + m * 2048 + k * 1024); } while (0)
; #define PG8_LDB(dst, b, h) do { _Pragma("unroll") for (int n = 0; n < 2; ++n) _Pragma("unroll") for (int k = 0; k < 2; ++k) dst[n][k] = *(const LAS bf16x8*)(lds + PG8_SB(b, h) + boff + n * 2048 + k * 1024); } while (0)
; #define PG8_MMA(ai, bj, At, Bt) do { __builtin_amdgcn_s_setprio(1); _Pragma("unroll") for (int m = 0; m < 4; ++m) _Pragma("unroll") for (int n = 0; n < 2; ++n) _Pragma("unroll") for (int k = 0; k < 2; ++k) \
;         acc[ai][bj][m][n] = __builtin_amdgcn_mfma_f32_16x16x32_bf16(Bt[n][k], At[m][k], acc[ai][bj][m][n], 0, 0, 0); __builtin_amdgcn_s_setprio(0); } while (0)
; #define PG8_WAIT_V(n) asm volatile("s_waitcnt vmcnt(" #n ")" ::: "memory")
; #define PG8_WAIT_L(n) asm volatile("s_waitcnt lgkmcnt(" #n ")" ::: "memory")
; #define PG8_BAR __builtin_amdgcn_s_barrier()
; #define PG8_SCHED __builtin_amdgcn_sched_barrier(0)
; template <class Epi>
; __device__ __forceinline__ void gemm_phase(LAS unsigned char* lds, const Gemm g, const StaticOrder& S, const Epi& E) {
;     ...
;             PG8_LDB(B0, 0, 0); PG8_LDB(B1, 0, 1); PG8_SCHED; PG8_LDA(At, 0, 0); PG8_STAGE(PG8_SA(1, 1), a1 + hstep, voffA);
;             PG8_WAIT_V(8); PG8_WAIT_L(0); PG8_BAR; PG8_MMA(0, 0, At, B0); PG8_MMA(0, 1, At, B1); PG8_BAR; PG8_SCHED;
;             PG8_LDA(At, 0, 1); PG8_STAGE(PG8_SB(0, 0), b2, voffB); PG8_STAGE(PG8_SB(0, 1), b2 + hstep, voffB); PG8_STAGE(PG8_SA(0, 0), a2, voffA);
;             PG8_WAIT_V(8); PG8_WAIT_L(0); PG8_BAR; PG8_MMA(1, 0, At, B0); PG8_MMA(1, 1, At, B1); PG8_BAR; PG8_SCHED;
.LBB0_191:
	s_add_u32 s22, s20, 0xfff80080
	s_addc_u32 s23, s21, -1
	s_add_i32 s55, 0, 0x10000
	s_cmp_eq_u32 s45, 28
	s_cselect_b32 s25, s15, s23
	s_cselect_b32 s24, s39, s22
	s_cselect_b32 s23, s13, s44
	s_cselect_b32 s22, s40, s41
	s_add_i32 s76, 0, 0x14000
	s_waitcnt lgkmcnt(0)
	v_add_u32_e32 v170, s55, v147
	v_add_u32_e32 v186, s76, v147
	ds_read_b128 v[132:135], v170
	ds_read_b128 v[162:165], v170 offset:1024
	ds_read_b128 v[166:169], v170 offset:2048
	ds_read_b128 v[170:173], v170 offset:3072
	ds_read_b128 v[174:177], v186
	ds_read_b128 v[178:181], v186 offset:1024
	ds_read_b128 v[182:185], v186 offset:2048
	ds_read_b128 v[186:189], v186 offset:3072
	v_lshl_add_u64 v[242:243], s[20:21], 0, v[158:159]
	s_add_i32 m0, s29, 0xc000
	ds_read_b128 v[190:193], v213
	ds_read_b128 v[214:217], v213 offset:1024
	ds_read_b128 v[218:221], v213 offset:2048
	ds_read_b128 v[222:225], v213 offset:3072
	ds_read_b128 v[226:229], v213 offset:4096
	ds_read_b128 v[230:233], v213 offset:5120
	ds_read_b128 v[234:237], v213 offset:6144
	ds_read_b128 v[238:241], v213 offset:7168
	global_load_lds_dwordx4 v[242:243], off
	v_lshl_add_u64 v[242:243], s[20:21], 0, v[160:161]
	s_add_i32 m0, s29, 0xe000
	s_nop 0
	global_load_lds_dwordx4 v[242:243], off
	s_waitcnt vmcnt(8)
	s_waitcnt lgkmcnt(0)
	s_setprio 1
	s_barrier
	v_mfma_f32_16x16x32_bf16 v[128:131], v[132:135], v[190:193], v[128:131]
	v_mfma_f32_16x16x32_bf16 v[124:127], v[166:169], v[190:193], v[124:127]
	v_mfma_f32_16x16x32_bf16 v[112:115], v[132:135], v[218:221], v[112:115]
	v_mfma_f32_16x16x32_bf16 v[108:111], v[166:169], v[218:221], v[108:111]
	v_mfma_f32_16x16x32_bf16 v[96:99], v[132:135], v[226:229], v[96:99]
	v_mfma_f32_16x16x32_bf16 v[92:95], v[166:169], v[226:229], v[92:95]
	v_mfma_f32_16x16x32_bf16 v[80:83], v[132:135], v[234:237], v[80:83]
	v_mfma_f32_16x16x32_bf16 v[76:79], v[166:169], v[234:237], v[76:79]
	v_mfma_f32_16x16x32_bf16 v[128:131], v[162:165], v[214:217], v[128:131]
	v_mfma_f32_16x16x32_bf16 v[124:127], v[170:173], v[214:217], v[124:127]
	v_mfma_f32_16x16x32_bf16 v[112:115], v[162:165], v[222:225], v[112:115]
	v_mfma_f32_16x16x32_bf16 v[108:111], v[170:173], v[222:225], v[108:111]
	v_mfma_f32_16x16x32_bf16 v[96:99], v[162:165], v[230:233], v[96:99]
	v_mfma_f32_16x16x32_bf16 v[92:95], v[170:173], v[230:233], v[92:95]
	v_mfma_f32_16x16x32_bf16 v[80:83], v[162:165], v[238:241], v[80:83]
	v_mfma_f32_16x16x32_bf16 v[76:79], v[170:173], v[238:241], v[76:79]
	v_mfma_f32_16x16x32_bf16 v[120:123], v[174:177], v[190:193], v[120:123]
	v_mfma_f32_16x16x32_bf16 v[116:119], v[182:185], v[190:193], v[116:119]
	v_mfma_f32_16x16x32_bf16 v[104:107], v[174:177], v[218:221], v[104:107]
	v_mfma_f32_16x16x32_bf16 v[100:103], v[182:185], v[218:221], v[100:103]
	v_mfma_f32_16x16x32_bf16 v[88:91], v[174:177], v[226:229], v[88:91]
	v_mfma_f32_16x16x32_bf16 v[84:87], v[182:185], v[226:229], v[84:87]
	v_mfma_f32_16x16x32_bf16 v[72:75], v[174:177], v[234:237], v[72:75]
	v_mfma_f32_16x16x32_bf16 v[68:71], v[182:185], v[234:237], v[68:71]
	v_mfma_f32_16x16x32_bf16 v[120:123], v[178:181], v[214:217], v[120:123]
	v_mfma_f32_16x16x32_bf16 v[116:119], v[186:189], v[214:217], v[116:119]
	v_mfma_f32_16x16x32_bf16 v[104:107], v[178:181], v[222:225], v[104:107]
	v_mfma_f32_16x16x32_bf16 v[100:103], v[186:189], v[222:225], v[100:103]
	v_mfma_f32_16x16x32_bf16 v[88:91], v[178:181], v[230:233], v[88:91]
	v_mfma_f32_16x16x32_bf16 v[84:87], v[186:189], v[230:233], v[84:87]
	v_mfma_f32_16x16x32_bf16 v[72:75], v[178:181], v[238:241], v[72:75]
	v_mfma_f32_16x16x32_bf16 v[68:71], v[186:189], v[238:241], v[68:71]
	s_barrier
	s_setprio 0
	s_add_i32 s55, s55, s28
	v_lshl_add_u64 v[242:243], s[22:23], 0, v[140:141]
	s_mov_b32 m0, s55
	ds_read_b128 v[190:193], v213 offset:16384
	ds_read_b128 v[214:217], v213 offset:17408
	ds_read_b128 v[218:221], v213 offset:18432
	ds_read_b128 v[222:225], v213 offset:19456
	ds_read_b128 v[226:229], v213 offset:20480
	ds_read_b128 v[230:233], v213 offset:21504
	ds_read_b128 v[234:237], v213 offset:22528
	ds_read_b128 v[238:241], v213 offset:23552
	global_load_lds_dwordx4 v[242:243], off
	s_add_i32 m0, s55, 0x2000
	s_add_u32 s74, s22, 0x80000
	v_lshl_add_u64 v[244:245], s[22:23], 0, v[136:137]
	s_addc_u32 s75, s23, 0
	s_add_i32 s55, s76, s28
	global_load_lds_dwordx4 v[244:245], off
	v_lshl_add_u64 v[246:247], s[74:75], 0, v[140:141]
	s_mov_b32 m0, s55
	v_lshl_add_u64 v[248:249], s[24:25], 0, v[138:139]
	global_load_lds_dwordx4 v[246:247], off
	v_lshl_add_u64 v[246:247], s[74:75], 0, v[136:137]
	s_add_i32 m0, s55, 0x2000
	s_nop 0
	global_load_lds_dwordx4 v[246:247], off
	v_lshl_add_u64 v[246:247], s[24:25], 0, v[156:157]
	s_mov_b32 m0, s29
	s_nop 0
	global_load_lds_dwordx4 v[246:247], off
	s_mov_b32 m0, s30
	s_nop 0
	global_load_lds_dwordx4 v[248:249], off
	s_waitcnt vmcnt(8)
	s_waitcnt lgkmcnt(0)
	s_setprio 1
	s_barrier
; #define PG8_STAGE(bufoff, gbase, voff) do { _Pragma("unroll") for (int _i = 0; _i < 2; ++_i) \
;         __builtin_amdgcn_global_load_lds((const unsigned*)((const char*)(gbase) + (voff)[_i]), (LAS unsigned*)(lds + (bufoff) + ldsw + _i * 8192), 16, 0, 0); } while (0)
; #define PG8_LDA(dst, b, h) do { _Pragma("unroll") for (int m = 0; m < 4; ++m) _Pragma("unroll") for (int k = 0; k < 2; ++k) dst[m][k] = *(const LAS bf16x8*)(lds + PG8_SA(b, h) + aoff + m * 2048 + k * 1024); } while (0)
; #define PG8_LDB(dst, b, h) do { _Pragma("unroll") for (int n = 0; n < 2; ++n) _Pragma("unroll") for (int k = 0; k < 2; ++k) dst[n][k] = *(const LAS bf16x8*)(lds + PG8_SB(b, h) + boff + n * 2048 + k * 1024); } while (0)
; #define PG8_MMA(ai, bj, At, Bt) do { __builtin_amdgcn_s_setprio(1); _Pragma("unroll") for (int m = 0; m < 4; ++m) _Pragma("unroll") for (int n = 0; n < 2; ++n) _Pragma("unroll") for (int k = 0; k < 2; ++k) \
;         acc[ai][bj][m][n] = __builtin_amdgcn_mfma_f32_16x16x32_bf16(Bt[n][k], At[m][k], acc[ai][bj][m][n], 0, 0, 0); __builtin_amdgcn_s_setprio(0); } while (0)
; #define PG8_WAIT_V(n) asm volatile("s_waitcnt vmcnt(" #n ")" ::: "memory")
; #define PG8_WAIT_L(n) asm volatile("s_waitcnt lgkmcnt(" #n ")" ::: "memory")
; #define PG8_BAR __builtin_amdgcn_s_barrier()
; #define PG8_SCHED __builtin_amdgcn_sched_barrier(0)
; template <class Epi>
; __device__ __forceinline__ void gemm_phase(LAS unsigned char* lds, const Gemm g, const StaticOrder& S, const Epi& E) {
;     ...
;             PG8_WAIT_V(8); PG8_WAIT_L(0); PG8_BAR; PG8_MMA(1, 0, At, B0); PG8_MMA(1, 1, At, B1); PG8_BAR; PG8_SCHED;
;             PG8_LDB(B0, 1, 0); PG8_LDB(B1, 1, 1); PG8_SCHED; PG8_LDA(At, 1, 0); PG8_STAGE(PG8_SA(0, 1), a2 + hstep, voffA);
;             PG8_WAIT_V(8); PG8_WAIT_L(0); PG8_BAR; PG8_MMA(0, 0, At, B0); PG8_MMA(0, 1, At, B1); PG8_BAR; PG8_SCHED;
	v_mfma_f32_16x16x32_bf16 v[64:67], v[132:135], v[190:193], v[64:67]
	v_mfma_f32_16x16x32_bf16 v[60:63], v[166:169], v[190:193], v[60:63]
	v_mfma_f32_16x16x32_bf16 v[48:51], v[132:135], v[218:221], v[48:51]
	v_mfma_f32_16x16x32_bf16 v[44:47], v[166:169], v[218:221], v[44:47]
	v_mfma_f32_16x16x32_bf16 v[32:35], v[132:135], v[226:229], v[32:35]
	v_mfma_f32_16x16x32_bf16 v[28:31], v[166:169], v[226:229], v[28:31]
	v_mfma_f32_16x16x32_bf16 v[16:19], v[132:135], v[234:237], v[16:19]
	v_mfma_f32_16x16x32_bf16 v[12:15], v[166:169], v[234:237], v[12:15]
	v_mfma_f32_16x16x32_bf16 v[64:67], v[162:165], v[214:217], v[64:67]
	v_mfma_f32_16x16x32_bf16 v[60:63], v[170:173], v[214:217], v[60:63]
	v_mfma_f32_16x16x32_bf16 v[48:51], v[162:165], v[222:225], v[48:51]
	v_mfma_f32_16x16x32_bf16 v[44:47], v[170:173], v[222:225], v[44:47]
	v_mfma_f32_16x16x32_bf16 v[32:35], v[162:165], v[230:233], v[32:35]
	v_mfma_f32_16x16x32_bf16 v[28:31], v[170:173], v[230:233], v[28:31]
	v_mfma_f32_16x16x32_bf16 v[16:19], v[162:165], v[238:241], v[16:19]
	v_mfma_f32_16x16x32_bf16 v[12:15], v[170:173], v[238:241], v[12:15]
	v_mfma_f32_16x16x32_bf16 v[56:59], v[174:177], v[190:193], v[56:59]
	v_mfma_f32_16x16x32_bf16 v[52:55], v[182:185], v[190:193], v[52:55]
	v_mfma_f32_16x16x32_bf16 v[40:43], v[174:177], v[218:221], v[40:43]
	v_mfma_f32_16x16x32_bf16 v[36:39], v[182:185], v[218:221], v[36:39]
	v_mfma_f32_16x16x32_bf16 v[24:27], v[174:177], v[226:229], v[24:27]
	v_mfma_f32_16x16x32_bf16 v[20:23], v[182:185], v[226:229], v[20:23]
	v_mfma_f32_16x16x32_bf16 v[8:11], v[174:177], v[234:237], v[8:11]
	v_mfma_f32_16x16x32_bf16 v[4:7], v[182:185], v[234:237], v[4:7]
	v_mfma_f32_16x16x32_bf16 v[56:59], v[178:181], v[214:217], v[56:59]
	v_mfma_f32_16x16x32_bf16 v[52:55], v[186:189], v[214:217], v[52:55]
	v_mfma_f32_16x16x32_bf16 v[40:43], v[178:181], v[222:225], v[40:43]
	v_mfma_f32_16x16x32_bf16 v[36:39], v[186:189], v[222:225], v[36:39]
	v_mfma_f32_16x16x32_bf16 v[24:27], v[178:181], v[230:233], v[24:27]
	v_mfma_f32_16x16x32_bf16 v[20:23], v[186:189], v[230:233], v[20:23]
	v_mfma_f32_16x16x32_bf16 v[8:11], v[178:181], v[238:241], v[8:11]
	v_mfma_f32_16x16x32_bf16 v[4:7], v[186:189], v[238:241], v[4:7]
	s_barrier
	s_setprio 0
	s_add_i32 s55, 0, 0x18000
	s_add_i32 s74, 0, 0x1c000
	v_add_u32_e32 v170, s55, v147
	v_add_u32_e32 v186, s74, v147
	ds_read_b128 v[132:135], v170
	ds_read_b128 v[162:165], v170 offset:1024
	ds_read_b128 v[166:169], v170 offset:2048
	ds_read_b128 v[170:173], v170 offset:3072
	ds_read_b128 v[174:177], v186
	ds_read_b128 v[178:181], v186 offset:1024
	ds_read_b128 v[182:185], v186 offset:2048
	ds_read_b128 v[186:189], v186 offset:3072
	s_add_u32 s24, s24, 0x80000
	s_addc_u32 s25, s25, 0
	s_mov_b32 m0, s31
	v_lshl_add_u64 v[250:251], s[24:25], 0, v[156:157]
	ds_read_b128 v[190:193], v213 offset:32768
	ds_read_b128 v[214:217], v213 offset:33792
	ds_read_b128 v[218:221], v213 offset:34816
	ds_read_b128 v[222:225], v213 offset:35840
	ds_read_b128 v[226:229], v213 offset:36864
	ds_read_b128 v[230:233], v213 offset:37888
	ds_read_b128 v[234:237], v213 offset:38912
	ds_read_b128 v[238:241], v213 offset:39936
	global_load_lds_dwordx4 v[250:251], off
	v_lshl_add_u64 v[250:251], s[24:25], 0, v[138:139]
	s_mov_b32 m0, s34
	s_nop 0
	global_load_lds_dwordx4 v[250:251], off
	s_waitcnt vmcnt(8)
	s_waitcnt lgkmcnt(0)
	s_setprio 1
	s_barrier
	v_mfma_f32_16x16x32_bf16 v[128:131], v[132:135], v[190:193], v[128:131]
	v_mfma_f32_16x16x32_bf16 v[124:127], v[166:169], v[190:193], v[124:127]
	v_mfma_f32_16x16x32_bf16 v[112:115], v[132:135], v[218:221], v[112:115]
	v_mfma_f32_16x16x32_bf16 v[108:111], v[166:169], v[218:221], v[108:111]
	v_mfma_f32_16x16x32_bf16 v[96:99], v[132:135], v[226:229], v[96:99]
	v_mfma_f32_16x16x32_bf16 v[92:95], v[166:169], v[226:229], v[92:95]
	v_mfma_f32_16x16x32_bf16 v[80:83], v[132:135], v[234:237], v[80:83]
	v_mfma_f32_16x16x32_bf16 v[76:79], v[166:169], v[234:237], v[76:79]
	v_mfma_f32_16x16x32_bf16 v[128:131], v[162:165], v[214:217], v[128:131]
	v_mfma_f32_16x16x32_bf16 v[124:127], v[170:173], v[214:217], v[124:127]
	v_mfma_f32_16x16x32_bf16 v[112:115], v[162:165], v[222:225], v[112:115]
	v_mfma_f32_16x16x32_bf16 v[108:111], v[170:173], v[222:225], v[108:111]
	v_mfma_f32_16x16x32_bf16 v[96:99], v[162:165], v[230:233], v[96:99]
	v_mfma_f32_16x16x32_bf16 v[92:95], v[170:173], v[230:233], v[92:95]
	v_mfma_f32_16x16x32_bf16 v[80:83], v[162:165], v[238:241], v[80:83]
	v_mfma_f32_16x16x32_bf16 v[76:79], v[170:173], v[238:241], v[76:79]
	v_mfma_f32_16x16x32_bf16 v[120:123], v[174:177], v[190:193], v[120:123]
	v_mfma_f32_16x16x32_bf16 v[116:119], v[182:185], v[190:193], v[116:119]
	v_mfma_f32_16x16x32_bf16 v[104:107], v[174:177], v[218:221], v[104:107]
	v_mfma_f32_16x16x32_bf16 v[100:103], v[182:185], v[218:221], v[100:103]
	v_mfma_f32_16x16x32_bf16 v[88:91], v[174:177], v[226:229], v[88:91]
	v_mfma_f32_16x16x32_bf16 v[84:87], v[182:185], v[226:229], v[84:87]
	v_mfma_f32_16x16x32_bf16 v[72:75], v[174:177], v[234:237], v[72:75]
	v_mfma_f32_16x16x32_bf16 v[68:71], v[182:185], v[234:237], v[68:71]
	v_mfma_f32_16x16x32_bf16 v[120:123], v[178:181], v[214:217], v[120:123]
	v_mfma_f32_16x16x32_bf16 v[116:119], v[186:189], v[214:217], v[116:119]
	v_mfma_f32_16x16x32_bf16 v[104:107], v[178:181], v[222:225], v[104:107]
	v_mfma_f32_16x16x32_bf16 v[100:103], v[186:189], v[222:225], v[100:103]
	v_mfma_f32_16x16x32_bf16 v[88:91], v[178:181], v[230:233], v[88:91]
	v_mfma_f32_16x16x32_bf16 v[84:87], v[186:189], v[230:233], v[84:87]
	v_mfma_f32_16x16x32_bf16 v[72:75], v[178:181], v[238:241], v[72:75]
	v_mfma_f32_16x16x32_bf16 v[68:71], v[186:189], v[238:241], v[68:71]
	s_barrier
; #define PG8_STAGE(bufoff, gbase, voff) do { _Pragma("unroll") for (int _i = 0; _i < 2; ++_i) \
;         __builtin_amdgcn_global_load_lds((const unsigned*)((const char*)(gbase) + (voff)[_i]), (LAS unsigned*)(lds + (bufoff) + ldsw + _i * 8192), 16, 0, 0); } while (0)
; #define PG8_LDA(dst, b, h) do { _Pragma("unroll") for (int m = 0; m < 4; ++m) _Pragma("unroll") for (int k = 0; k < 2; ++k) dst[m][k] = *(const LAS bf16x8*)(lds + PG8_SA(b, h) + aoff + m * 2048 + k * 1024); } while (0)
; #define PG8_MMA(ai, bj, At, Bt) do { __builtin_amdgcn_s_setprio(1); _Pragma("unroll") for (int m = 0; m < 4; ++m) _Pragma("unroll") for (int n = 0; n < 2; ++n) _Pragma("unroll") for (int k = 0; k < 2; ++k) \
;         acc[ai][bj][m][n] = __builtin_amdgcn_mfma_f32_16x16x32_bf16(Bt[n][k], At[m][k], acc[ai][bj][m][n], 0, 0, 0); __builtin_amdgcn_s_setprio(0); } while (0)
; #define PG8_WAIT_V(n) asm volatile("s_waitcnt vmcnt(" #n ")" ::: "memory")
; #define PG8_WAIT_L(n) asm volatile("s_waitcnt lgkmcnt(" #n ")" ::: "memory")
; #define PG8_BAR __builtin_amdgcn_s_barrier()
; #define PG8_SCHED __builtin_amdgcn_sched_barrier(0)
; template <class Epi>
; __device__ __forceinline__ void gemm_phase(LAS unsigned char* lds, const Gemm g, const StaticOrder& S, const Epi& E) {
;     ...
;             PG8_LDA(At, 1, 1); PG8_STAGE(PG8_SB(1, 0), b3, voffB); PG8_STAGE(PG8_SB(1, 1), b3 + hstep, voffB); PG8_STAGE(PG8_SA(1, 0), a3, voffA);
;             PG8_WAIT_V(8); PG8_WAIT_L(0); PG8_BAR; PG8_MMA(1, 0, At, B0); PG8_MMA(1, 1, At, B1); PG8_BAR; PG8_SCHED;
;         }
	s_setprio 0
	s_add_i32 s24, s55, s28
	v_lshl_add_u64 v[242:243], v[242:243], 0, s[68:69]
	s_mov_b32 m0, s24
	ds_read_b128 v[190:193], v213 offset:49152
	ds_read_b128 v[214:217], v213 offset:50176
	ds_read_b128 v[218:221], v213 offset:51200
	ds_read_b128 v[222:225], v213 offset:52224
	ds_read_b128 v[226:229], v213 offset:53248
	ds_read_b128 v[230:233], v213 offset:54272
	ds_read_b128 v[234:237], v213 offset:55296
	ds_read_b128 v[238:241], v213 offset:56320
	global_load_lds_dwordx4 v[242:243], off
	s_add_i32 m0, s24, 0x2000
	s_add_u32 s22, s22, 0x80080
	v_lshl_add_u64 v[242:243], v[244:245], 0, s[68:69]
	s_addc_u32 s23, s23, 0
	s_add_i32 s24, s74, s28
	global_load_lds_dwordx4 v[242:243], off
	v_lshl_add_u64 v[242:243], s[22:23], 0, v[140:141]
	s_mov_b32 m0, s24
	s_nop 0
	global_load_lds_dwordx4 v[242:243], off
	v_lshl_add_u64 v[242:243], s[22:23], 0, v[136:137]
	s_add_i32 m0, s24, 0x2000
	s_nop 0
	global_load_lds_dwordx4 v[242:243], off
	v_lshl_add_u64 v[242:243], v[246:247], 0, s[68:69]
	s_mov_b32 m0, s35
	s_nop 0
	global_load_lds_dwordx4 v[242:243], off
	v_lshl_add_u64 v[242:243], v[248:249], 0, s[68:69]
	s_mov_b32 m0, s36
	s_nop 0
	global_load_lds_dwordx4 v[242:243], off
	s_waitcnt vmcnt(8)
	s_waitcnt lgkmcnt(0)
	s_setprio 1
	s_barrier
	v_mfma_f32_16x16x32_bf16 v[64:67], v[132:135], v[190:193], v[64:67]
	v_mfma_f32_16x16x32_bf16 v[60:63], v[166:169], v[190:193], v[60:63]
	v_mfma_f32_16x16x32_bf16 v[48:51], v[132:135], v[218:221], v[48:51]
	v_mfma_f32_16x16x32_bf16 v[44:47], v[166:169], v[218:221], v[44:47]
	v_mfma_f32_16x16x32_bf16 v[32:35], v[132:135], v[226:229], v[32:35]
	v_mfma_f32_16x16x32_bf16 v[28:31], v[166:169], v[226:229], v[28:31]
	v_mfma_f32_16x16x32_bf16 v[16:19], v[132:135], v[234:237], v[16:19]
	v_mfma_f32_16x16x32_bf16 v[12:15], v[166:169], v[234:237], v[12:15]
	v_mfma_f32_16x16x32_bf16 v[64:67], v[162:165], v[214:217], v[64:67]
	v_mfma_f32_16x16x32_bf16 v[60:63], v[170:173], v[214:217], v[60:63]
	v_mfma_f32_16x16x32_bf16 v[48:51], v[162:165], v[222:225], v[48:51]
	v_mfma_f32_16x16x32_bf16 v[44:47], v[170:173], v[222:225], v[44:47]
	v_mfma_f32_16x16x32_bf16 v[32:35], v[162:165], v[230:233], v[32:35]
	v_mfma_f32_16x16x32_bf16 v[28:31], v[170:173], v[230:233], v[28:31]
	v_mfma_f32_16x16x32_bf16 v[16:19], v[162:165], v[238:241], v[16:19]
	v_mfma_f32_16x16x32_bf16 v[12:15], v[170:173], v[238:241], v[12:15]
	v_mfma_f32_16x16x32_bf16 v[56:59], v[174:177], v[190:193], v[56:59]
	v_mfma_f32_16x16x32_bf16 v[52:55], v[182:185], v[190:193], v[52:55]
	v_mfma_f32_16x16x32_bf16 v[40:43], v[174:177], v[218:221], v[40:43]
	v_mfma_f32_16x16x32_bf16 v[36:39], v[182:185], v[218:221], v[36:39]
	v_mfma_f32_16x16x32_bf16 v[24:27], v[174:177], v[226:229], v[24:27]
	v_mfma_f32_16x16x32_bf16 v[20:23], v[182:185], v[226:229], v[20:23]
	v_mfma_f32_16x16x32_bf16 v[8:11], v[174:177], v[234:237], v[8:11]
	v_mfma_f32_16x16x32_bf16 v[4:7], v[182:185], v[234:237], v[4:7]
	v_mfma_f32_16x16x32_bf16 v[56:59], v[178:181], v[214:217], v[56:59]
	v_mfma_f32_16x16x32_bf16 v[52:55], v[186:189], v[214:217], v[52:55]
	v_mfma_f32_16x16x32_bf16 v[40:43], v[178:181], v[222:225], v[40:43]
	v_mfma_f32_16x16x32_bf16 v[36:39], v[186:189], v[222:225], v[36:39]
	v_mfma_f32_16x16x32_bf16 v[24:27], v[178:181], v[230:233], v[24:27]
	v_mfma_f32_16x16x32_bf16 v[20:23], v[186:189], v[230:233], v[20:23]
	v_mfma_f32_16x16x32_bf16 v[8:11], v[178:181], v[238:241], v[8:11]
	v_mfma_f32_16x16x32_bf16 v[4:7], v[186:189], v[238:241], v[4:7]
	s_barrier
	s_setprio 0
	s_add_i32 s45, s45, 2
	s_add_u32 s20, s20, 0x100
	s_addc_u32 s21, s21, 0
	s_add_u32 s41, s41, 0x100
	s_addc_u32 s44, s44, 0
	s_cmp_gt_u32 s45, 29
	s_cbranch_scc0 .LBB0_191
	s_and_b64 vcc, exec, s[10:11]
	s_cbranch_vccz .LBB0_194
	s_barrier

; #define PG8_STAGE(bufoff, gbase, voff) do { _Pragma("unroll") for (int _i = 0; _i < 2; ++_i) \
;         __builtin_amdgcn_global_load_lds((const unsigned*)((const char*)(gbase) + (voff)[_i]), (LAS unsigned*)(lds + (bufoff) + ldsw + _i * 8192), 16, 0, 0); } while (0)
; #define PG8_LDA(dst, b, h) do { _Pragma("unroll") for (int m = 0; m < 4; ++m) _Pragma("unroll") for (int k = 0; k < 2; ++k) dst[m][k] = *(const LAS bf16x8*)(lds + PG8_SA(b, h) + aoff + m * 2048 + k * 1024); } while (0)
; #define PG8_LDB(dst, b, h) do { _Pragma("unroll") for (int n = 0; n < 2; ++n) _Pragma("unroll") for (int k = 0; k < 2; ++k) dst[n][k] = *(const LAS bf16x8*)(lds + PG8_SB(b, h) + boff + n * 2048 + k * 1024); } while (0)
; #define PG8_MMA(ai, bj, At, Bt) do { __builtin_amdgcn_s_setprio(1); _Pragma("unroll") for (int m = 0; m < 4; ++m) _Pragma("unroll") for (int n = 0; n < 2; ++n) _Pragma("unroll") for (int k = 0; k < 2; ++k) \
;         acc[ai][bj][m][n] = __builtin_amdgcn_mfma_f32_16x16x32_bf16(Bt[n][k], At[m][k], acc[ai][bj][m][n], 0, 0, 0); __builtin_amdgcn_s_setprio(0); } while (0)
; #define PG8_WAIT_V(n) asm volatile("s_waitcnt vmcnt(" #n ")" ::: "memory")
; #define PG8_WAIT_L(n) asm volatile("s_waitcnt lgkmcnt(" #n ")" ::: "memory")
; #define PG8_BAR __builtin_amdgcn_s_barrier()
; #define PG8_SCHED __builtin_amdgcn_sched_barrier(0)
; template <class Epi>
; __device__ __forceinline__ void gemm_phase(LAS unsigned char* lds, const Gemm g, const StaticOrder& S, const Epi& E) {
;     ...
;             PG8_LDB(B0, 0, 0); PG8_LDB(B1, 0, 1); PG8_SCHED; PG8_LDA(At, 0, 0); PG8_STAGE(PG8_SA(1, 1), a1 + hstep, voffA);
;             PG8_WAIT_V(8); PG8_WAIT_L(0); PG8_BAR; PG8_MMA(0, 0, At, B0); PG8_MMA(0, 1, At, B1); PG8_BAR; PG8_SCHED;
;             PG8_LDA(At, 0, 1); PG8_STAGE(PG8_SB(0, 0), b2, voffB); PG8_STAGE(PG8_SB(0, 1), b2 + hstep, voffB); PG8_STAGE(PG8_SA(0, 0), a2, voffA);
;             PG8_WAIT_V(8); PG8_WAIT_L(0); PG8_BAR; PG8_MMA(1, 0, At, B0); PG8_MMA(1, 1, At, B1); PG8_BAR; PG8_SCHED;
.LBB0_1591:
	s_add_u32 s14, s12, 0xfffc0080
	s_addc_u32 s15, s13, -1
	s_add_i32 s78, 0, 0x10000
	s_cmp_eq_u32 s88, 12
	s_cselect_b32 s29, s23, s15
	s_cselect_b32 s28, s75, s14
	v_add_u32_e32 v3, s78, v176
	s_cselect_b32 s15, s21, s80
	s_cselect_b32 s14, s76, s77
	s_add_i32 s89, 0, 0x14000
	ds_read_b128 v[134:137], v3
	ds_read_b128 v[138:141], v3 offset:1024
	ds_read_b128 v[168:171], v3 offset:2048
	ds_read_b128 v[172:175], v3 offset:3072
	v_add_u32_e32 v3, s89, v176
	ds_read_b128 v[180:183], v3
	ds_read_b128 v[184:187], v3 offset:1024
	ds_read_b128 v[188:191], v3 offset:2048
	ds_read_b128 v[212:215], v3 offset:3072
	v_lshl_add_u64 v[4:5], s[12:13], 0, v[164:165]
	s_add_i32 m0, s37, 0xc000
	ds_read_b128 v[216:219], v178
	ds_read_b128 v[220:223], v178 offset:1024
	ds_read_b128 v[224:227], v178 offset:2048
	ds_read_b128 v[228:231], v178 offset:3072
	ds_read_b128 v[232:235], v178 offset:4096
	ds_read_b128 v[236:239], v178 offset:5120
	ds_read_b128 v[240:243], v178 offset:6144
	ds_read_b128 v[244:247], v178 offset:7168
	global_load_lds_dwordx4 v[4:5], off
	v_lshl_add_u64 v[4:5], s[12:13], 0, v[166:167]
	s_add_i32 m0, s37, 0xe000
	s_nop 0
	global_load_lds_dwordx4 v[4:5], off
	s_waitcnt vmcnt(8)
	s_waitcnt lgkmcnt(0)
	s_setprio 1
	s_barrier
	v_mfma_f32_16x16x32_bf16 v[130:133], v[134:137], v[216:219], v[130:133]
	v_mfma_f32_16x16x32_bf16 v[126:129], v[168:171], v[216:219], v[126:129]
	v_mfma_f32_16x16x32_bf16 v[122:125], v[134:137], v[224:227], v[122:125]
	v_mfma_f32_16x16x32_bf16 v[118:121], v[168:171], v[224:227], v[118:121]
	v_mfma_f32_16x16x32_bf16 v[114:117], v[134:137], v[232:235], v[114:117]
	v_mfma_f32_16x16x32_bf16 v[110:113], v[168:171], v[232:235], v[110:113]
	v_mfma_f32_16x16x32_bf16 v[106:109], v[134:137], v[240:243], v[106:109]
	v_mfma_f32_16x16x32_bf16 v[102:105], v[168:171], v[240:243], v[102:105]
	v_mfma_f32_16x16x32_bf16 v[130:133], v[138:141], v[220:223], v[130:133]
	v_mfma_f32_16x16x32_bf16 v[126:129], v[172:175], v[220:223], v[126:129]
	v_mfma_f32_16x16x32_bf16 v[122:125], v[138:141], v[228:231], v[122:125]
	v_mfma_f32_16x16x32_bf16 v[118:121], v[172:175], v[228:231], v[118:121]
	v_mfma_f32_16x16x32_bf16 v[114:117], v[138:141], v[236:239], v[114:117]
	v_mfma_f32_16x16x32_bf16 v[110:113], v[172:175], v[236:239], v[110:113]
	v_mfma_f32_16x16x32_bf16 v[106:109], v[138:141], v[244:247], v[106:109]
	v_mfma_f32_16x16x32_bf16 v[102:105], v[172:175], v[244:247], v[102:105]
	v_mfma_f32_16x16x32_bf16 v[98:101], v[180:183], v[216:219], v[98:101]
	v_mfma_f32_16x16x32_bf16 v[94:97], v[188:191], v[216:219], v[94:97]
	v_mfma_f32_16x16x32_bf16 v[90:93], v[180:183], v[224:227], v[90:93]
	v_mfma_f32_16x16x32_bf16 v[86:89], v[188:191], v[224:227], v[86:89]
	v_mfma_f32_16x16x32_bf16 v[82:85], v[180:183], v[232:235], v[82:85]
	v_mfma_f32_16x16x32_bf16 v[78:81], v[188:191], v[232:235], v[78:81]
	v_mfma_f32_16x16x32_bf16 v[74:77], v[180:183], v[240:243], v[74:77]
	v_mfma_f32_16x16x32_bf16 v[70:73], v[188:191], v[240:243], v[70:73]
	v_mfma_f32_16x16x32_bf16 v[98:101], v[184:187], v[220:223], v[98:101]
	v_mfma_f32_16x16x32_bf16 v[94:97], v[212:215], v[220:223], v[94:97]
	v_mfma_f32_16x16x32_bf16 v[90:93], v[184:187], v[228:231], v[90:93]
	v_mfma_f32_16x16x32_bf16 v[86:89], v[212:215], v[228:231], v[86:89]
	v_mfma_f32_16x16x32_bf16 v[82:85], v[184:187], v[236:239], v[82:85]
	v_mfma_f32_16x16x32_bf16 v[78:81], v[212:215], v[236:239], v[78:81]
	v_mfma_f32_16x16x32_bf16 v[74:77], v[184:187], v[244:247], v[74:77]
	v_mfma_f32_16x16x32_bf16 v[70:73], v[212:215], v[244:247], v[70:73]
	s_barrier
	s_setprio 0
	s_add_i32 s78, s78, s34
	v_lshl_add_u64 v[192:193], s[14:15], 0, v[160:161]
	s_mov_b32 m0, s78
	ds_read_b128 v[216:219], v178 offset:16384
	ds_read_b128 v[220:223], v178 offset:17408
	ds_read_b128 v[224:227], v178 offset:18432
	ds_read_b128 v[228:231], v178 offset:19456
	ds_read_b128 v[232:235], v178 offset:20480
	ds_read_b128 v[236:239], v178 offset:21504
	ds_read_b128 v[240:243], v178 offset:22528
	ds_read_b128 v[244:247], v178 offset:23552
	global_load_lds_dwordx4 v[192:193], off
	s_add_i32 m0, s78, 0x2000
	s_add_u32 s78, s14, 0x40000
	v_lshl_add_u64 v[248:249], s[14:15], 0, v[156:157]
	s_addc_u32 s79, s15, 0
	s_add_i32 s89, s89, s34
	global_load_lds_dwordx4 v[248:249], off
	v_lshl_add_u64 v[4:5], s[78:79], 0, v[160:161]
	s_mov_b32 m0, s89
	v_lshl_add_u64 v[250:251], s[28:29], 0, v[162:163]
	global_load_lds_dwordx4 v[4:5], off
	v_lshl_add_u64 v[4:5], s[78:79], 0, v[156:157]
	s_add_i32 m0, s89, 0x2000
	v_lshl_add_u64 v[198:199], s[28:29], 0, v[158:159]
	global_load_lds_dwordx4 v[4:5], off
	s_mov_b32 m0, s37
	s_nop 0
	global_load_lds_dwordx4 v[250:251], off
	s_mov_b32 m0, s38
	s_nop 0
	global_load_lds_dwordx4 v[198:199], off
	s_waitcnt vmcnt(8)
	s_waitcnt lgkmcnt(0)
	s_setprio 1
	s_barrier
; #define PG8_STAGE(bufoff, gbase, voff) do { _Pragma("unroll") for (int _i = 0; _i < 2; ++_i) \
;         __builtin_amdgcn_global_load_lds((const unsigned*)((const char*)(gbase) + (voff)[_i]), (LAS unsigned*)(lds + (bufoff) + ldsw + _i * 8192), 16, 0, 0); } while (0)
; #define PG8_LDA(dst, b, h) do { _Pragma("unroll") for (int m = 0; m < 4; ++m) _Pragma("unroll") for (int k = 0; k < 2; ++k) dst[m][k] = *(const LAS bf16x8*)(lds + PG8_SA(b, h) + aoff + m * 2048 + k * 1024); } while (0)
; #define PG8_LDB(dst, b, h) do { _Pragma("unroll") for (int n = 0; n < 2; ++n) _Pragma("unroll") for (int k = 0; k < 2; ++k) dst[n][k] = *(const LAS bf16x8*)(lds + PG8_SB(b, h) + boff + n * 2048 + k * 1024); } while (0)
; #define PG8_MMA(ai, bj, At, Bt) do { __builtin_amdgcn_s_setprio(1); _Pragma("unroll") for (int m = 0; m < 4; ++m) _Pragma("unroll") for (int n = 0; n < 2; ++n) _Pragma("unroll") for (int k = 0; k < 2; ++k) \
;         acc[ai][bj][m][n] = __builtin_amdgcn_mfma_f32_16x16x32_bf16(Bt[n][k], At[m][k], acc[ai][bj][m][n], 0, 0, 0); __builtin_amdgcn_s_setprio(0); } while (0)
; #define PG8_WAIT_V(n) asm volatile("s_waitcnt vmcnt(" #n ")" ::: "memory")
; #define PG8_WAIT_L(n) asm volatile("s_waitcnt lgkmcnt(" #n ")" ::: "memory")
; #define PG8_BAR __builtin_amdgcn_s_barrier()
; #define PG8_SCHED __builtin_amdgcn_sched_barrier(0)
; template <class Epi>
; __device__ __forceinline__ void gemm_phase(LAS unsigned char* lds, const Gemm g, const StaticOrder& S, const Epi& E) {
;     ...
;             PG8_WAIT_V(8); PG8_WAIT_L(0); PG8_BAR; PG8_MMA(1, 0, At, B0); PG8_MMA(1, 1, At, B1); PG8_BAR; PG8_SCHED;
;             PG8_LDB(B0, 1, 0); PG8_LDB(B1, 1, 1); PG8_SCHED; PG8_LDA(At, 1, 0); PG8_STAGE(PG8_SA(0, 1), a2 + hstep, voffA);
;             PG8_WAIT_V(8); PG8_WAIT_L(0); PG8_BAR; PG8_MMA(0, 0, At, B0); PG8_MMA(0, 1, At, B1); PG8_BAR; PG8_SCHED;
	v_mfma_f32_16x16x32_bf16 v[66:69], v[134:137], v[216:219], v[66:69]
	v_mfma_f32_16x16x32_bf16 v[62:65], v[168:171], v[216:219], v[62:65]
	v_mfma_f32_16x16x32_bf16 v[58:61], v[134:137], v[224:227], v[58:61]
	v_mfma_f32_16x16x32_bf16 v[54:57], v[168:171], v[224:227], v[54:57]
	v_mfma_f32_16x16x32_bf16 v[50:53], v[134:137], v[232:235], v[50:53]
	v_mfma_f32_16x16x32_bf16 v[46:49], v[168:171], v[232:235], v[46:49]
	v_mfma_f32_16x16x32_bf16 v[42:45], v[134:137], v[240:243], v[42:45]
	v_mfma_f32_16x16x32_bf16 v[38:41], v[168:171], v[240:243], v[38:41]
	v_mfma_f32_16x16x32_bf16 v[66:69], v[138:141], v[220:223], v[66:69]
	v_mfma_f32_16x16x32_bf16 v[62:65], v[172:175], v[220:223], v[62:65]
	v_mfma_f32_16x16x32_bf16 v[58:61], v[138:141], v[228:231], v[58:61]
	v_mfma_f32_16x16x32_bf16 v[54:57], v[172:175], v[228:231], v[54:57]
	v_mfma_f32_16x16x32_bf16 v[50:53], v[138:141], v[236:239], v[50:53]
	v_mfma_f32_16x16x32_bf16 v[46:49], v[172:175], v[236:239], v[46:49]
	v_mfma_f32_16x16x32_bf16 v[42:45], v[138:141], v[244:247], v[42:45]
	v_mfma_f32_16x16x32_bf16 v[38:41], v[172:175], v[244:247], v[38:41]
	v_mfma_f32_16x16x32_bf16 v[34:37], v[180:183], v[216:219], v[34:37]
	v_mfma_f32_16x16x32_bf16 v[30:33], v[188:191], v[216:219], v[30:33]
	v_mfma_f32_16x16x32_bf16 v[26:29], v[180:183], v[224:227], v[26:29]
	v_mfma_f32_16x16x32_bf16 v[22:25], v[188:191], v[224:227], v[22:25]
	v_mfma_f32_16x16x32_bf16 v[18:21], v[180:183], v[232:235], v[18:21]
	v_mfma_f32_16x16x32_bf16 v[14:17], v[188:191], v[232:235], v[14:17]
	v_mfma_f32_16x16x32_bf16 v[10:13], v[180:183], v[240:243], v[10:13]
	v_mfma_f32_16x16x32_bf16 v[4:7], v[188:191], v[240:243], v[6:9]
	v_mfma_f32_16x16x32_bf16 v[34:37], v[184:187], v[220:223], v[34:37]
	v_mfma_f32_16x16x32_bf16 v[30:33], v[212:215], v[220:223], v[30:33]
	v_mfma_f32_16x16x32_bf16 v[26:29], v[184:187], v[228:231], v[26:29]
	v_mfma_f32_16x16x32_bf16 v[22:25], v[212:215], v[228:231], v[22:25]
	v_mfma_f32_16x16x32_bf16 v[18:21], v[184:187], v[236:239], v[18:21]
	v_mfma_f32_16x16x32_bf16 v[14:17], v[212:215], v[236:239], v[14:17]
	v_mfma_f32_16x16x32_bf16 v[10:13], v[184:187], v[244:247], v[10:13]
	v_mfma_f32_16x16x32_bf16 v[4:7], v[212:215], v[244:247], v[4:7]
	s_barrier
	s_setprio 0
	s_add_i32 s78, 0, 0x18000
	v_add_u32_e32 v3, s78, v176
	s_add_i32 s79, 0, 0x1c000
	ds_read_b128 v[134:137], v3
	ds_read_b128 v[138:141], v3 offset:1024
	ds_read_b128 v[168:171], v3 offset:2048
	ds_read_b128 v[172:175], v3 offset:3072
	v_add_u32_e32 v3, s79, v176
	ds_read_b128 v[180:183], v3
	ds_read_b128 v[184:187], v3 offset:1024
	ds_read_b128 v[188:191], v3 offset:2048
	ds_read_b128 v[212:215], v3 offset:3072
	s_add_u32 s28, s28, 0x40000
	s_addc_u32 s29, s29, 0
	s_mov_b32 m0, s39
	v_lshl_add_u64 v[8:9], s[28:29], 0, v[162:163]
	ds_read_b128 v[216:219], v178 offset:32768
	ds_read_b128 v[220:223], v178 offset:33792
	ds_read_b128 v[224:227], v178 offset:34816
	ds_read_b128 v[228:231], v178 offset:35840
	ds_read_b128 v[232:235], v178 offset:36864
	ds_read_b128 v[236:239], v178 offset:37888
	ds_read_b128 v[240:243], v178 offset:38912
	ds_read_b128 v[244:247], v178 offset:39936
	global_load_lds_dwordx4 v[8:9], off
	v_lshl_add_u64 v[8:9], s[28:29], 0, v[158:159]
	s_mov_b32 m0, s40
	s_nop 0
	global_load_lds_dwordx4 v[8:9], off
	s_waitcnt vmcnt(8)
	s_waitcnt lgkmcnt(0)
	s_setprio 1
	s_barrier
	v_mfma_f32_16x16x32_bf16 v[130:133], v[134:137], v[216:219], v[130:133]
	v_mfma_f32_16x16x32_bf16 v[126:129], v[168:171], v[216:219], v[126:129]
	v_mfma_f32_16x16x32_bf16 v[122:125], v[134:137], v[224:227], v[122:125]
	v_mfma_f32_16x16x32_bf16 v[118:121], v[168:171], v[224:227], v[118:121]
	v_mfma_f32_16x16x32_bf16 v[114:117], v[134:137], v[232:235], v[114:117]
	v_mfma_f32_16x16x32_bf16 v[110:113], v[168:171], v[232:235], v[110:113]
	v_mfma_f32_16x16x32_bf16 v[106:109], v[134:137], v[240:243], v[106:109]
	v_mfma_f32_16x16x32_bf16 v[102:105], v[168:171], v[240:243], v[102:105]
	v_mfma_f32_16x16x32_bf16 v[130:133], v[138:141], v[220:223], v[130:133]
	v_mfma_f32_16x16x32_bf16 v[126:129], v[172:175], v[220:223], v[126:129]
	v_mfma_f32_16x16x32_bf16 v[122:125], v[138:141], v[228:231], v[122:125]
	v_mfma_f32_16x16x32_bf16 v[118:121], v[172:175], v[228:231], v[118:121]
	v_mfma_f32_16x16x32_bf16 v[114:117], v[138:141], v[236:239], v[114:117]
	v_mfma_f32_16x16x32_bf16 v[110:113], v[172:175], v[236:239], v[110:113]
	v_mfma_f32_16x16x32_bf16 v[106:109], v[138:141], v[244:247], v[106:109]
	v_mfma_f32_16x16x32_bf16 v[102:105], v[172:175], v[244:247], v[102:105]
	v_mfma_f32_16x16x32_bf16 v[98:101], v[180:183], v[216:219], v[98:101]
	v_mfma_f32_16x16x32_bf16 v[94:97], v[188:191], v[216:219], v[94:97]
	v_mfma_f32_16x16x32_bf16 v[90:93], v[180:183], v[224:227], v[90:93]
	v_mfma_f32_16x16x32_bf16 v[86:89], v[188:191], v[224:227], v[86:89]
	v_mfma_f32_16x16x32_bf16 v[82:85], v[180:183], v[232:235], v[82:85]
	v_mfma_f32_16x16x32_bf16 v[78:81], v[188:191], v[232:235], v[78:81]
	v_mfma_f32_16x16x32_bf16 v[74:77], v[180:183], v[240:243], v[74:77]
	v_mfma_f32_16x16x32_bf16 v[70:73], v[188:191], v[240:243], v[70:73]
	v_mfma_f32_16x16x32_bf16 v[98:101], v[184:187], v[220:223], v[98:101]
	v_mfma_f32_16x16x32_bf16 v[94:97], v[212:215], v[220:223], v[94:97]
	v_mfma_f32_16x16x32_bf16 v[90:93], v[184:187], v[228:231], v[90:93]
	v_mfma_f32_16x16x32_bf16 v[86:89], v[212:215], v[228:231], v[86:89]
	v_mfma_f32_16x16x32_bf16 v[82:85], v[184:187], v[236:239], v[82:85]
	v_mfma_f32_16x16x32_bf16 v[78:81], v[212:215], v[236:239], v[78:81]
	v_mfma_f32_16x16x32_bf16 v[74:77], v[184:187], v[244:247], v[74:77]
	v_mfma_f32_16x16x32_bf16 v[70:73], v[212:215], v[244:247], v[70:73]
	s_barrier
; #define PG8_STAGE(bufoff, gbase, voff) do { _Pragma("unroll") for (int _i = 0; _i < 2; ++_i) \
;         __builtin_amdgcn_global_load_lds((const unsigned*)((const char*)(gbase) + (voff)[_i]), (LAS unsigned*)(lds + (bufoff) + ldsw + _i * 8192), 16, 0, 0); } while (0)
; #define PG8_LDA(dst, b, h) do { _Pragma("unroll") for (int m = 0; m < 4; ++m) _Pragma("unroll") for (int k = 0; k < 2; ++k) dst[m][k] = *(const LAS bf16x8*)(lds + PG8_SA(b, h) + aoff + m * 2048 + k * 1024); } while (0)
; #define PG8_MMA(ai, bj, At, Bt) do { __builtin_amdgcn_s_setprio(1); _Pragma("unroll") for (int m = 0; m < 4; ++m) _Pragma("unroll") for (int n = 0; n < 2; ++n) _Pragma("unroll") for (int k = 0; k < 2; ++k) \
;         acc[ai][bj][m][n] = __builtin_amdgcn_mfma_f32_16x16x32_bf16(Bt[n][k], At[m][k], acc[ai][bj][m][n], 0, 0, 0); __builtin_amdgcn_s_setprio(0); } while (0)
; #define PG8_WAIT_V(n) asm volatile("s_waitcnt vmcnt(" #n ")" ::: "memory")
; #define PG8_WAIT_L(n) asm volatile("s_waitcnt lgkmcnt(" #n ")" ::: "memory")
; #define PG8_BAR __builtin_amdgcn_s_barrier()
; #define PG8_SCHED __builtin_amdgcn_sched_barrier(0)
; template <class Epi>
; __device__ __forceinline__ void gemm_phase(LAS unsigned char* lds, const Gemm g, const StaticOrder& S, const Epi& E) {
;     ...
;             PG8_LDA(At, 1, 1); PG8_STAGE(PG8_SB(1, 0), b3, voffB); PG8_STAGE(PG8_SB(1, 1), b3 + hstep, voffB); PG8_STAGE(PG8_SA(1, 0), a3, voffA);
;             PG8_WAIT_V(8); PG8_WAIT_L(0); PG8_BAR; PG8_MMA(1, 0, At, B0); PG8_MMA(1, 1, At, B1); PG8_BAR; PG8_SCHED;
;         }
	s_setprio 0
	s_add_i32 s28, s78, s34
	v_lshl_add_u64 v[8:9], v[192:193], 0, s[68:69]
	s_mov_b32 m0, s28
	ds_read_b128 v[216:219], v178 offset:49152
	ds_read_b128 v[220:223], v178 offset:50176
	ds_read_b128 v[224:227], v178 offset:51200
	ds_read_b128 v[228:231], v178 offset:52224
	ds_read_b128 v[232:235], v178 offset:53248
	ds_read_b128 v[236:239], v178 offset:54272
	ds_read_b128 v[240:243], v178 offset:55296
	ds_read_b128 v[244:247], v178 offset:56320
	global_load_lds_dwordx4 v[8:9], off
	s_add_i32 m0, s28, 0x2000
	s_add_u32 s14, s14, 0x40080
	v_lshl_add_u64 v[8:9], v[248:249], 0, s[68:69]
	s_addc_u32 s15, s15, 0
	s_add_i32 s28, s79, s34
	global_load_lds_dwordx4 v[8:9], off
	v_lshl_add_u64 v[8:9], s[14:15], 0, v[160:161]
	s_mov_b32 m0, s28
	s_nop 0
	global_load_lds_dwordx4 v[8:9], off
	v_lshl_add_u64 v[8:9], s[14:15], 0, v[156:157]
	s_add_i32 m0, s28, 0x2000
	s_nop 0
	global_load_lds_dwordx4 v[8:9], off
	v_lshl_add_u64 v[8:9], v[250:251], 0, s[68:69]
	s_mov_b32 m0, s41
	s_nop 0
	global_load_lds_dwordx4 v[8:9], off
	v_lshl_add_u64 v[8:9], v[198:199], 0, s[68:69]
	s_mov_b32 m0, s44
	s_nop 0
	global_load_lds_dwordx4 v[8:9], off
	s_waitcnt vmcnt(8)
	s_waitcnt lgkmcnt(0)
	s_setprio 1
	s_barrier
	v_mfma_f32_16x16x32_bf16 v[66:69], v[134:137], v[216:219], v[66:69]
	v_mfma_f32_16x16x32_bf16 v[62:65], v[168:171], v[216:219], v[62:65]
	v_mfma_f32_16x16x32_bf16 v[58:61], v[134:137], v[224:227], v[58:61]
	v_mfma_f32_16x16x32_bf16 v[54:57], v[168:171], v[224:227], v[54:57]
	v_mfma_f32_16x16x32_bf16 v[50:53], v[134:137], v[232:235], v[50:53]
	v_mfma_f32_16x16x32_bf16 v[46:49], v[168:171], v[232:235], v[46:49]
	v_mfma_f32_16x16x32_bf16 v[42:45], v[134:137], v[240:243], v[42:45]
	v_mfma_f32_16x16x32_bf16 v[38:41], v[168:171], v[240:243], v[38:41]
	v_mfma_f32_16x16x32_bf16 v[66:69], v[138:141], v[220:223], v[66:69]
	v_mfma_f32_16x16x32_bf16 v[62:65], v[172:175], v[220:223], v[62:65]
	v_mfma_f32_16x16x32_bf16 v[58:61], v[138:141], v[228:231], v[58:61]
	v_mfma_f32_16x16x32_bf16 v[54:57], v[172:175], v[228:231], v[54:57]
	v_mfma_f32_16x16x32_bf16 v[50:53], v[138:141], v[236:239], v[50:53]
	v_mfma_f32_16x16x32_bf16 v[46:49], v[172:175], v[236:239], v[46:49]
	v_mfma_f32_16x16x32_bf16 v[42:45], v[138:141], v[244:247], v[42:45]
	v_mfma_f32_16x16x32_bf16 v[38:41], v[172:175], v[244:247], v[38:41]
	v_mfma_f32_16x16x32_bf16 v[34:37], v[180:183], v[216:219], v[34:37]
	v_mfma_f32_16x16x32_bf16 v[30:33], v[188:191], v[216:219], v[30:33]
	v_mfma_f32_16x16x32_bf16 v[26:29], v[180:183], v[224:227], v[26:29]
	v_mfma_f32_16x16x32_bf16 v[22:25], v[188:191], v[224:227], v[22:25]
	v_mfma_f32_16x16x32_bf16 v[18:21], v[180:183], v[232:235], v[18:21]
	v_mfma_f32_16x16x32_bf16 v[14:17], v[188:191], v[232:235], v[14:17]
	v_mfma_f32_16x16x32_bf16 v[8:11], v[180:183], v[240:243], v[10:13]
	v_mfma_f32_16x16x32_bf16 v[4:7], v[188:191], v[240:243], v[4:7]
	v_mfma_f32_16x16x32_bf16 v[34:37], v[184:187], v[220:223], v[34:37]
	v_mfma_f32_16x16x32_bf16 v[30:33], v[212:215], v[220:223], v[30:33]
	v_mfma_f32_16x16x32_bf16 v[26:29], v[184:187], v[228:231], v[26:29]
	v_mfma_f32_16x16x32_bf16 v[22:25], v[212:215], v[228:231], v[22:25]
	v_mfma_f32_16x16x32_bf16 v[18:21], v[184:187], v[236:239], v[18:21]
	v_mfma_f32_16x16x32_bf16 v[14:17], v[212:215], v[236:239], v[14:17]
	v_mfma_f32_16x16x32_bf16 v[10:13], v[184:187], v[244:247], v[8:11]
	v_mfma_f32_16x16x32_bf16 v[6:9], v[212:215], v[244:247], v[4:7]
	s_barrier
	s_setprio 0
	s_add_i32 s88, s88, 2
	s_add_u32 s12, s12, 0x100
	s_addc_u32 s13, s13, 0
	s_add_u32 s77, s77, 0x100
	s_addc_u32 s80, s80, 0
	s_cmp_gt_u32 s88, 13
	s_cbranch_scc0 .LBB0_1591
	s_and_b64 vcc, exec, s[18:19]
	s_cbranch_vccz .LBB0_1594
	s_barrier

; #define PG8_STAGE(bufoff, gbase, voff) do { _Pragma("unroll") for (int _i = 0; _i < 2; ++_i) \
;         __builtin_amdgcn_global_load_lds((const unsigned*)((const char*)(gbase) + (voff)[_i]), (LAS unsigned*)(lds + (bufoff) + ldsw + _i * 8192), 16, 0, 0); } while (0)
; #define PG8_LDA(dst, b, h) do { _Pragma("unroll") for (int m = 0; m < 4; ++m) _Pragma("unroll") for (int k = 0; k < 2; ++k) dst[m][k] = *(const LAS bf16x8*)(lds + PG8_SA(b, h) + aoff + m * 2048 + k * 1024); } while (0)
; #define PG8_LDB(dst, b, h) do { _Pragma("unroll") for (int n = 0; n < 2; ++n) _Pragma("unroll") for (int k = 0; k < 2; ++k) dst[n][k] = *(const LAS bf16x8*)(lds + PG8_SB(b, h) + boff + n * 2048 + k * 1024); } while (0)
; #define PG8_MMA(ai, bj, At, Bt) do { __builtin_amdgcn_s_setprio(1); _Pragma("unroll") for (int m = 0; m < 4; ++m) _Pragma("unroll") for (int n = 0; n < 2; ++n) _Pragma("unroll") for (int k = 0; k < 2; ++k) \
;         acc[ai][bj][m][n] = __builtin_amdgcn_mfma_f32_16x16x32_bf16(Bt[n][k], At[m][k], acc[ai][bj][m][n], 0, 0, 0); __builtin_amdgcn_s_setprio(0); } while (0)
; #define PG8_WAIT_V(n) asm volatile("s_waitcnt vmcnt(" #n ")" ::: "memory")
; #define PG8_WAIT_L(n) asm volatile("s_waitcnt lgkmcnt(" #n ")" ::: "memory")
; #define PG8_BAR __builtin_amdgcn_s_barrier()
; #define PG8_SCHED __builtin_amdgcn_sched_barrier(0)
; template <class Epi>
; __device__ __forceinline__ void gemm_phase(LAS unsigned char* lds, const Gemm g, const StaticOrder& S, const Epi& E) {
;     ...
;             PG8_LDB(B0, 0, 0); PG8_LDB(B1, 0, 1); PG8_SCHED; PG8_LDA(At, 0, 0); PG8_STAGE(PG8_SA(1, 1), a1 + hstep, voffA);
;             PG8_WAIT_V(8); PG8_WAIT_L(0); PG8_BAR; PG8_MMA(0, 0, At, B0); PG8_MMA(0, 1, At, B1); PG8_BAR; PG8_SCHED;
;             PG8_LDA(At, 0, 1); PG8_STAGE(PG8_SB(0, 0), b2, voffB); PG8_STAGE(PG8_SB(0, 1), b2 + hstep, voffB); PG8_STAGE(PG8_SA(0, 0), a2, voffA);
;             PG8_WAIT_V(8); PG8_WAIT_L(0); PG8_BAR; PG8_MMA(1, 0, At, B0); PG8_MMA(1, 1, At, B1); PG8_BAR; PG8_SCHED;
.LBB0_1741:
	s_add_u32 s28, s26, 0xfff80080
	s_addc_u32 s29, s27, -1
	s_add_i32 s78, 0, 0x10000
	s_cmp_eq_u32 s80, 28
	s_cselect_b32 s31, s21, s29
	s_cselect_b32 s30, s74, s28
	v_add_u32_e32 v162, s78, v147
	s_cselect_b32 s29, s19, s77
	s_cselect_b32 s28, s75, s76
	s_add_i32 s88, 0, 0x14000
	ds_read_b128 v[158:161], v162
	ds_read_b128 v[166:169], v162 offset:1024
	ds_read_b128 v[170:173], v162 offset:2048
	ds_read_b128 v[174:177], v162 offset:3072
	v_add_u32_e32 v162, s88, v147
	ds_read_b128 v[178:181], v162
	ds_read_b128 v[182:185], v162 offset:1024
	ds_read_b128 v[186:189], v162 offset:2048
	ds_read_b128 v[190:193], v162 offset:3072
	v_lshl_add_u64 v[162:163], s[26:27], 0, v[140:141]
	s_add_i32 m0, s35, 0xc000
	ds_read_b128 v[212:215], v165
	ds_read_b128 v[216:219], v165 offset:1024
	ds_read_b128 v[220:223], v165 offset:2048
	ds_read_b128 v[224:227], v165 offset:3072
	ds_read_b128 v[228:231], v165 offset:4096
	ds_read_b128 v[232:235], v165 offset:5120
	ds_read_b128 v[236:239], v165 offset:6144
	ds_read_b128 v[240:243], v165 offset:7168
	global_load_lds_dwordx4 v[162:163], off
	v_lshl_add_u64 v[162:163], s[26:27], 0, v[156:157]
	s_add_i32 m0, s35, 0xe000
	s_nop 0
	global_load_lds_dwordx4 v[162:163], off
	s_waitcnt vmcnt(8)
	s_waitcnt lgkmcnt(0)
	s_setprio 1
	s_barrier
	v_mfma_f32_16x16x32_bf16 v[128:131], v[158:161], v[212:215], v[128:131]
	v_mfma_f32_16x16x32_bf16 v[124:127], v[170:173], v[212:215], v[124:127]
	v_mfma_f32_16x16x32_bf16 v[112:115], v[158:161], v[220:223], v[112:115]
	v_mfma_f32_16x16x32_bf16 v[108:111], v[170:173], v[220:223], v[108:111]
	v_mfma_f32_16x16x32_bf16 v[96:99], v[158:161], v[228:231], v[96:99]
	v_mfma_f32_16x16x32_bf16 v[92:95], v[170:173], v[228:231], v[92:95]
	v_mfma_f32_16x16x32_bf16 v[80:83], v[158:161], v[236:239], v[80:83]
	v_mfma_f32_16x16x32_bf16 v[76:79], v[170:173], v[236:239], v[76:79]
	v_mfma_f32_16x16x32_bf16 v[128:131], v[166:169], v[216:219], v[128:131]
	v_mfma_f32_16x16x32_bf16 v[124:127], v[174:177], v[216:219], v[124:127]
	v_mfma_f32_16x16x32_bf16 v[112:115], v[166:169], v[224:227], v[112:115]
	v_mfma_f32_16x16x32_bf16 v[108:111], v[174:177], v[224:227], v[108:111]
	v_mfma_f32_16x16x32_bf16 v[96:99], v[166:169], v[232:235], v[96:99]
	v_mfma_f32_16x16x32_bf16 v[92:95], v[174:177], v[232:235], v[92:95]
	v_mfma_f32_16x16x32_bf16 v[80:83], v[166:169], v[240:243], v[80:83]
	v_mfma_f32_16x16x32_bf16 v[76:79], v[174:177], v[240:243], v[76:79]
	v_mfma_f32_16x16x32_bf16 v[120:123], v[178:181], v[212:215], v[120:123]
	v_mfma_f32_16x16x32_bf16 v[116:119], v[186:189], v[212:215], v[116:119]
	v_mfma_f32_16x16x32_bf16 v[104:107], v[178:181], v[220:223], v[104:107]
	v_mfma_f32_16x16x32_bf16 v[100:103], v[186:189], v[220:223], v[100:103]
	v_mfma_f32_16x16x32_bf16 v[88:91], v[178:181], v[228:231], v[88:91]
	v_mfma_f32_16x16x32_bf16 v[84:87], v[186:189], v[228:231], v[84:87]
	v_mfma_f32_16x16x32_bf16 v[72:75], v[178:181], v[236:239], v[72:75]
	v_mfma_f32_16x16x32_bf16 v[68:71], v[186:189], v[236:239], v[68:71]
	v_mfma_f32_16x16x32_bf16 v[120:123], v[182:185], v[216:219], v[120:123]
	v_mfma_f32_16x16x32_bf16 v[116:119], v[190:193], v[216:219], v[116:119]
	v_mfma_f32_16x16x32_bf16 v[104:107], v[182:185], v[224:227], v[104:107]
	v_mfma_f32_16x16x32_bf16 v[100:103], v[190:193], v[224:227], v[100:103]
	v_mfma_f32_16x16x32_bf16 v[88:91], v[182:185], v[232:235], v[88:91]
	v_mfma_f32_16x16x32_bf16 v[84:87], v[190:193], v[232:235], v[84:87]
	v_mfma_f32_16x16x32_bf16 v[72:75], v[182:185], v[240:243], v[72:75]
	v_mfma_f32_16x16x32_bf16 v[68:71], v[190:193], v[240:243], v[68:71]
	s_barrier
	s_setprio 0
	s_add_i32 s78, s78, s34
	v_lshl_add_u64 v[162:163], s[28:29], 0, v[136:137]
	s_mov_b32 m0, s78
	ds_read_b128 v[212:215], v165 offset:16384
	ds_read_b128 v[216:219], v165 offset:17408
	ds_read_b128 v[220:223], v165 offset:18432
	ds_read_b128 v[224:227], v165 offset:19456
	ds_read_b128 v[228:231], v165 offset:20480
	ds_read_b128 v[232:235], v165 offset:21504
	ds_read_b128 v[236:239], v165 offset:22528
	ds_read_b128 v[240:243], v165 offset:23552
	global_load_lds_dwordx4 v[162:163], off
	s_add_i32 m0, s78, 0x2000
	s_add_u32 s78, s28, 0x80000
	v_lshl_add_u64 v[198:199], s[28:29], 0, v[132:133]
	s_addc_u32 s79, s29, 0
	s_add_i32 s88, s88, s34
	global_load_lds_dwordx4 v[198:199], off
	v_lshl_add_u64 v[244:245], s[78:79], 0, v[136:137]
	s_mov_b32 m0, s88
	v_lshl_add_u64 v[246:247], s[30:31], 0, v[134:135]
	global_load_lds_dwordx4 v[244:245], off
	v_lshl_add_u64 v[244:245], s[78:79], 0, v[132:133]
	s_add_i32 m0, s88, 0x2000
	s_nop 0
	global_load_lds_dwordx4 v[244:245], off
	v_lshl_add_u64 v[244:245], s[30:31], 0, v[138:139]
	s_mov_b32 m0, s35
	s_nop 0
	global_load_lds_dwordx4 v[244:245], off
	s_mov_b32 m0, s36
	s_nop 0
	global_load_lds_dwordx4 v[246:247], off
	s_waitcnt vmcnt(8)
	s_waitcnt lgkmcnt(0)
	s_setprio 1
	s_barrier
; #define PG8_STAGE(bufoff, gbase, voff) do { _Pragma("unroll") for (int _i = 0; _i < 2; ++_i) \
;         __builtin_amdgcn_global_load_lds((const unsigned*)((const char*)(gbase) + (voff)[_i]), (LAS unsigned*)(lds + (bufoff) + ldsw + _i * 8192), 16, 0, 0); } while (0)
; #define PG8_LDA(dst, b, h) do { _Pragma("unroll") for (int m = 0; m < 4; ++m) _Pragma("unroll") for (int k = 0; k < 2; ++k) dst[m][k] = *(const LAS bf16x8*)(lds + PG8_SA(b, h) + aoff + m * 2048 + k * 1024); } while (0)
; #define PG8_LDB(dst, b, h) do { _Pragma("unroll") for (int n = 0; n < 2; ++n) _Pragma("unroll") for (int k = 0; k < 2; ++k) dst[n][k] = *(const LAS bf16x8*)(lds + PG8_SB(b, h) + boff + n * 2048 + k * 1024); } while (0)
; #define PG8_MMA(ai, bj, At, Bt) do { __builtin_amdgcn_s_setprio(1); _Pragma("unroll") for (int m = 0; m < 4; ++m) _Pragma("unroll") for (int n = 0; n < 2; ++n) _Pragma("unroll") for (int k = 0; k < 2; ++k) \
;         acc[ai][bj][m][n] = __builtin_amdgcn_mfma_f32_16x16x32_bf16(Bt[n][k], At[m][k], acc[ai][bj][m][n], 0, 0, 0); __builtin_amdgcn_s_setprio(0); } while (0)
; #define PG8_WAIT_V(n) asm volatile("s_waitcnt vmcnt(" #n ")" ::: "memory")
; #define PG8_WAIT_L(n) asm volatile("s_waitcnt lgkmcnt(" #n ")" ::: "memory")
; #define PG8_BAR __builtin_amdgcn_s_barrier()
; #define PG8_SCHED __builtin_amdgcn_sched_barrier(0)
; template <class Epi>
; __device__ __forceinline__ void gemm_phase(LAS unsigned char* lds, const Gemm g, const StaticOrder& S, const Epi& E) {
;     ...
;             PG8_WAIT_V(8); PG8_WAIT_L(0); PG8_BAR; PG8_MMA(1, 0, At, B0); PG8_MMA(1, 1, At, B1); PG8_BAR; PG8_SCHED;
;             PG8_LDB(B0, 1, 0); PG8_LDB(B1, 1, 1); PG8_SCHED; PG8_LDA(At, 1, 0); PG8_STAGE(PG8_SA(0, 1), a2 + hstep, voffA);
;             PG8_WAIT_V(8); PG8_WAIT_L(0); PG8_BAR; PG8_MMA(0, 0, At, B0); PG8_MMA(0, 1, At, B1); PG8_BAR; PG8_SCHED;
	v_mfma_f32_16x16x32_bf16 v[64:67], v[158:161], v[212:215], v[64:67]
	v_mfma_f32_16x16x32_bf16 v[60:63], v[170:173], v[212:215], v[60:63]
	v_mfma_f32_16x16x32_bf16 v[48:51], v[158:161], v[220:223], v[48:51]
	v_mfma_f32_16x16x32_bf16 v[44:47], v[170:173], v[220:223], v[44:47]
	v_mfma_f32_16x16x32_bf16 v[32:35], v[158:161], v[228:231], v[32:35]
	v_mfma_f32_16x16x32_bf16 v[28:31], v[170:173], v[228:231], v[28:31]
	v_mfma_f32_16x16x32_bf16 v[16:19], v[158:161], v[236:239], v[16:19]
	v_mfma_f32_16x16x32_bf16 v[12:15], v[170:173], v[236:239], v[12:15]
	v_mfma_f32_16x16x32_bf16 v[64:67], v[166:169], v[216:219], v[64:67]
	v_mfma_f32_16x16x32_bf16 v[60:63], v[174:177], v[216:219], v[60:63]
	v_mfma_f32_16x16x32_bf16 v[48:51], v[166:169], v[224:227], v[48:51]
	v_mfma_f32_16x16x32_bf16 v[44:47], v[174:177], v[224:227], v[44:47]
	v_mfma_f32_16x16x32_bf16 v[32:35], v[166:169], v[232:235], v[32:35]
	v_mfma_f32_16x16x32_bf16 v[28:31], v[174:177], v[232:235], v[28:31]
	v_mfma_f32_16x16x32_bf16 v[16:19], v[166:169], v[240:243], v[16:19]
	v_mfma_f32_16x16x32_bf16 v[12:15], v[174:177], v[240:243], v[12:15]
	v_mfma_f32_16x16x32_bf16 v[56:59], v[178:181], v[212:215], v[56:59]
	v_mfma_f32_16x16x32_bf16 v[52:55], v[186:189], v[212:215], v[52:55]
	v_mfma_f32_16x16x32_bf16 v[40:43], v[178:181], v[220:223], v[40:43]
	v_mfma_f32_16x16x32_bf16 v[36:39], v[186:189], v[220:223], v[36:39]
	v_mfma_f32_16x16x32_bf16 v[24:27], v[178:181], v[228:231], v[24:27]
	v_mfma_f32_16x16x32_bf16 v[20:23], v[186:189], v[228:231], v[20:23]
	v_mfma_f32_16x16x32_bf16 v[8:11], v[178:181], v[236:239], v[8:11]
	v_mfma_f32_16x16x32_bf16 v[4:7], v[186:189], v[236:239], v[4:7]
	v_mfma_f32_16x16x32_bf16 v[56:59], v[182:185], v[216:219], v[56:59]
	v_mfma_f32_16x16x32_bf16 v[52:55], v[190:193], v[216:219], v[52:55]
	v_mfma_f32_16x16x32_bf16 v[40:43], v[182:185], v[224:227], v[40:43]
	v_mfma_f32_16x16x32_bf16 v[36:39], v[190:193], v[224:227], v[36:39]
	v_mfma_f32_16x16x32_bf16 v[24:27], v[182:185], v[232:235], v[24:27]
	v_mfma_f32_16x16x32_bf16 v[20:23], v[190:193], v[232:235], v[20:23]
	v_mfma_f32_16x16x32_bf16 v[8:11], v[182:185], v[240:243], v[8:11]
	v_mfma_f32_16x16x32_bf16 v[4:7], v[190:193], v[240:243], v[4:7]
	s_barrier
	s_setprio 0
	s_add_i32 s78, 0, 0x18000
	s_add_i32 s79, 0, 0x1c000
	v_add_u32_e32 v174, s78, v147
	v_add_u32_e32 v190, s79, v147
	ds_read_b128 v[158:161], v174
	ds_read_b128 v[166:169], v174 offset:1024
	ds_read_b128 v[170:173], v174 offset:2048
	ds_read_b128 v[174:177], v174 offset:3072
	ds_read_b128 v[178:181], v190
	ds_read_b128 v[182:185], v190 offset:1024
	ds_read_b128 v[186:189], v190 offset:2048
	ds_read_b128 v[190:193], v190 offset:3072
	s_add_u32 s30, s30, 0x80000
	s_addc_u32 s31, s31, 0
	s_mov_b32 m0, s37
	v_lshl_add_u64 v[248:249], s[30:31], 0, v[138:139]
	ds_read_b128 v[212:215], v165 offset:32768
	ds_read_b128 v[216:219], v165 offset:33792
	ds_read_b128 v[220:223], v165 offset:34816
	ds_read_b128 v[224:227], v165 offset:35840
	ds_read_b128 v[228:231], v165 offset:36864
	ds_read_b128 v[232:235], v165 offset:37888
	ds_read_b128 v[236:239], v165 offset:38912
	ds_read_b128 v[240:243], v165 offset:39936
	global_load_lds_dwordx4 v[248:249], off
	v_lshl_add_u64 v[248:249], s[30:31], 0, v[134:135]
	s_mov_b32 m0, s38
	s_nop 0
	global_load_lds_dwordx4 v[248:249], off
	s_waitcnt vmcnt(8)
	s_waitcnt lgkmcnt(0)
	s_setprio 1
	s_barrier
	v_mfma_f32_16x16x32_bf16 v[128:131], v[158:161], v[212:215], v[128:131]
	v_mfma_f32_16x16x32_bf16 v[124:127], v[170:173], v[212:215], v[124:127]
	v_mfma_f32_16x16x32_bf16 v[112:115], v[158:161], v[220:223], v[112:115]
	v_mfma_f32_16x16x32_bf16 v[108:111], v[170:173], v[220:223], v[108:111]
	v_mfma_f32_16x16x32_bf16 v[96:99], v[158:161], v[228:231], v[96:99]
	v_mfma_f32_16x16x32_bf16 v[92:95], v[170:173], v[228:231], v[92:95]
	v_mfma_f32_16x16x32_bf16 v[80:83], v[158:161], v[236:239], v[80:83]
	v_mfma_f32_16x16x32_bf16 v[76:79], v[170:173], v[236:239], v[76:79]
	v_mfma_f32_16x16x32_bf16 v[128:131], v[166:169], v[216:219], v[128:131]
	v_mfma_f32_16x16x32_bf16 v[124:127], v[174:177], v[216:219], v[124:127]
	v_mfma_f32_16x16x32_bf16 v[112:115], v[166:169], v[224:227], v[112:115]
	v_mfma_f32_16x16x32_bf16 v[108:111], v[174:177], v[224:227], v[108:111]
	v_mfma_f32_16x16x32_bf16 v[96:99], v[166:169], v[232:235], v[96:99]
	v_mfma_f32_16x16x32_bf16 v[92:95], v[174:177], v[232:235], v[92:95]
	v_mfma_f32_16x16x32_bf16 v[80:83], v[166:169], v[240:243], v[80:83]
	v_mfma_f32_16x16x32_bf16 v[76:79], v[174:177], v[240:243], v[76:79]
	v_mfma_f32_16x16x32_bf16 v[120:123], v[178:181], v[212:215], v[120:123]
	v_mfma_f32_16x16x32_bf16 v[116:119], v[186:189], v[212:215], v[116:119]
	v_mfma_f32_16x16x32_bf16 v[104:107], v[178:181], v[220:223], v[104:107]
	v_mfma_f32_16x16x32_bf16 v[100:103], v[186:189], v[220:223], v[100:103]
	v_mfma_f32_16x16x32_bf16 v[88:91], v[178:181], v[228:231], v[88:91]
	v_mfma_f32_16x16x32_bf16 v[84:87], v[186:189], v[228:231], v[84:87]
	v_mfma_f32_16x16x32_bf16 v[72:75], v[178:181], v[236:239], v[72:75]
	v_mfma_f32_16x16x32_bf16 v[68:71], v[186:189], v[236:239], v[68:71]
	v_mfma_f32_16x16x32_bf16 v[120:123], v[182:185], v[216:219], v[120:123]
	v_mfma_f32_16x16x32_bf16 v[116:119], v[190:193], v[216:219], v[116:119]
	v_mfma_f32_16x16x32_bf16 v[104:107], v[182:185], v[224:227], v[104:107]
	v_mfma_f32_16x16x32_bf16 v[100:103], v[190:193], v[224:227], v[100:103]
	v_mfma_f32_16x16x32_bf16 v[88:91], v[182:185], v[232:235], v[88:91]
	v_mfma_f32_16x16x32_bf16 v[84:87], v[190:193], v[232:235], v[84:87]
	v_mfma_f32_16x16x32_bf16 v[72:75], v[182:185], v[240:243], v[72:75]
	v_mfma_f32_16x16x32_bf16 v[68:71], v[190:193], v[240:243], v[68:71]
	s_barrier
; #define PG8_STAGE(bufoff, gbase, voff) do { _Pragma("unroll") for (int _i = 0; _i < 2; ++_i) \
;         __builtin_amdgcn_global_load_lds((const unsigned*)((const char*)(gbase) + (voff)[_i]), (LAS unsigned*)(lds + (bufoff) + ldsw + _i * 8192), 16, 0, 0); } while (0)
; #define PG8_LDA(dst, b, h) do { _Pragma("unroll") for (int m = 0; m < 4; ++m) _Pragma("unroll") for (int k = 0; k < 2; ++k) dst[m][k] = *(const LAS bf16x8*)(lds + PG8_SA(b, h) + aoff + m * 2048 + k * 1024); } while (0)
; #define PG8_MMA(ai, bj, At, Bt) do { __builtin_amdgcn_s_setprio(1); _Pragma("unroll") for (int m = 0; m < 4; ++m) _Pragma("unroll") for (int n = 0; n < 2; ++n) _Pragma("unroll") for (int k = 0; k < 2; ++k) \
;         acc[ai][bj][m][n] = __builtin_amdgcn_mfma_f32_16x16x32_bf16(Bt[n][k], At[m][k], acc[ai][bj][m][n], 0, 0, 0); __builtin_amdgcn_s_setprio(0); } while (0)
; #define PG8_WAIT_V(n) asm volatile("s_waitcnt vmcnt(" #n ")" ::: "memory")
; #define PG8_WAIT_L(n) asm volatile("s_waitcnt lgkmcnt(" #n ")" ::: "memory")
; #define PG8_BAR __builtin_amdgcn_s_barrier()
; #define PG8_SCHED __builtin_amdgcn_sched_barrier(0)
; template <class Epi>
; __device__ __forceinline__ void gemm_phase(LAS unsigned char* lds, const Gemm g, const StaticOrder& S, const Epi& E) {
;     ...
;             PG8_LDA(At, 1, 1); PG8_STAGE(PG8_SB(1, 0), b3, voffB); PG8_STAGE(PG8_SB(1, 1), b3 + hstep, voffB); PG8_STAGE(PG8_SA(1, 0), a3, voffA);
;             PG8_WAIT_V(8); PG8_WAIT_L(0); PG8_BAR; PG8_MMA(1, 0, At, B0); PG8_MMA(1, 1, At, B1); PG8_BAR; PG8_SCHED;
;         }
;         if (wr == 0) PG8_BAR;
	s_setprio 0
	s_add_i32 s30, s78, s34
	v_lshl_add_u64 v[162:163], v[162:163], 0, s[68:69]
	s_mov_b32 m0, s30
	ds_read_b128 v[212:215], v165 offset:49152
	ds_read_b128 v[216:219], v165 offset:50176
	ds_read_b128 v[220:223], v165 offset:51200
	ds_read_b128 v[224:227], v165 offset:52224
	ds_read_b128 v[228:231], v165 offset:53248
	ds_read_b128 v[232:235], v165 offset:54272
	ds_read_b128 v[236:239], v165 offset:55296
	ds_read_b128 v[240:243], v165 offset:56320
	global_load_lds_dwordx4 v[162:163], off
	s_add_i32 m0, s30, 0x2000
	s_add_u32 s28, s28, 0x80080
	v_lshl_add_u64 v[162:163], v[198:199], 0, s[68:69]
	s_addc_u32 s29, s29, 0
	s_add_i32 s30, s79, s34
	global_load_lds_dwordx4 v[162:163], off
	v_lshl_add_u64 v[162:163], s[28:29], 0, v[136:137]
	s_mov_b32 m0, s30
	s_nop 0
	global_load_lds_dwordx4 v[162:163], off
	v_lshl_add_u64 v[162:163], s[28:29], 0, v[132:133]
	s_add_i32 m0, s30, 0x2000
	s_nop 0
	global_load_lds_dwordx4 v[162:163], off
	v_lshl_add_u64 v[162:163], v[244:245], 0, s[68:69]
	s_mov_b32 m0, s40
	s_nop 0
	global_load_lds_dwordx4 v[162:163], off
	v_lshl_add_u64 v[162:163], v[246:247], 0, s[68:69]
	s_mov_b32 m0, s41
	s_nop 0
	global_load_lds_dwordx4 v[162:163], off
	s_waitcnt vmcnt(8)
	s_waitcnt lgkmcnt(0)
	s_setprio 1
	s_barrier
	v_mfma_f32_16x16x32_bf16 v[64:67], v[158:161], v[212:215], v[64:67]
	v_mfma_f32_16x16x32_bf16 v[60:63], v[170:173], v[212:215], v[60:63]
	v_mfma_f32_16x16x32_bf16 v[48:51], v[158:161], v[220:223], v[48:51]
	v_mfma_f32_16x16x32_bf16 v[44:47], v[170:173], v[220:223], v[44:47]
	v_mfma_f32_16x16x32_bf16 v[32:35], v[158:161], v[228:231], v[32:35]
	v_mfma_f32_16x16x32_bf16 v[28:31], v[170:173], v[228:231], v[28:31]
	v_mfma_f32_16x16x32_bf16 v[16:19], v[158:161], v[236:239], v[16:19]
	v_mfma_f32_16x16x32_bf16 v[12:15], v[170:173], v[236:239], v[12:15]
	v_mfma_f32_16x16x32_bf16 v[64:67], v[166:169], v[216:219], v[64:67]
	v_mfma_f32_16x16x32_bf16 v[60:63], v[174:177], v[216:219], v[60:63]
	v_mfma_f32_16x16x32_bf16 v[48:51], v[166:169], v[224:227], v[48:51]
	v_mfma_f32_16x16x32_bf16 v[44:47], v[174:177], v[224:227], v[44:47]
	v_mfma_f32_16x16x32_bf16 v[32:35], v[166:169], v[232:235], v[32:35]
	v_mfma_f32_16x16x32_bf16 v[28:31], v[174:177], v[232:235], v[28:31]
	v_mfma_f32_16x16x32_bf16 v[16:19], v[166:169], v[240:243], v[16:19]
	v_mfma_f32_16x16x32_bf16 v[12:15], v[174:177], v[240:243], v[12:15]
	v_mfma_f32_16x16x32_bf16 v[56:59], v[178:181], v[212:215], v[56:59]
	v_mfma_f32_16x16x32_bf16 v[52:55], v[186:189], v[212:215], v[52:55]
	v_mfma_f32_16x16x32_bf16 v[40:43], v[178:181], v[220:223], v[40:43]
	v_mfma_f32_16x16x32_bf16 v[36:39], v[186:189], v[220:223], v[36:39]
	v_mfma_f32_16x16x32_bf16 v[24:27], v[178:181], v[228:231], v[24:27]
	v_mfma_f32_16x16x32_bf16 v[20:23], v[186:189], v[228:231], v[20:23]
	v_mfma_f32_16x16x32_bf16 v[8:11], v[178:181], v[236:239], v[8:11]
	v_mfma_f32_16x16x32_bf16 v[4:7], v[186:189], v[236:239], v[4:7]
	v_mfma_f32_16x16x32_bf16 v[56:59], v[182:185], v[216:219], v[56:59]
	v_mfma_f32_16x16x32_bf16 v[52:55], v[190:193], v[216:219], v[52:55]
	v_mfma_f32_16x16x32_bf16 v[40:43], v[182:185], v[224:227], v[40:43]
	v_mfma_f32_16x16x32_bf16 v[36:39], v[190:193], v[224:227], v[36:39]
	v_mfma_f32_16x16x32_bf16 v[24:27], v[182:185], v[232:235], v[24:27]
	v_mfma_f32_16x16x32_bf16 v[20:23], v[190:193], v[232:235], v[20:23]
	v_mfma_f32_16x16x32_bf16 v[8:11], v[182:185], v[240:243], v[8:11]
	v_mfma_f32_16x16x32_bf16 v[4:7], v[190:193], v[240:243], v[4:7]
	s_barrier
	s_setprio 0
	s_add_i32 s80, s80, 2
	s_add_u32 s26, s26, 0x100
	s_addc_u32 s27, s27, 0
	s_add_u32 s76, s76, 0x100
	s_addc_u32 s77, s77, 0
	s_cmp_gt_u32 s80, 29
	s_cbranch_scc0 .LBB0_1741
	s_and_b64 vcc, exec, s[16:17]
	s_cbranch_vccz .LBB0_1744
	s_barrier

; #define PG8_STAGE(bufoff, gbase, voff) do { _Pragma("unroll") for (int _i = 0; _i < 2; ++_i) \
;         __builtin_amdgcn_global_load_lds((const unsigned*)((const char*)(gbase) + (voff)[_i]), (LAS unsigned*)(lds + (bufoff) + ldsw + _i * 8192), 16, 0, 0); } while (0)
; #define PG8_LDA(dst, b, h) do { _Pragma("unroll") for (int m = 0; m < 4; ++m) _Pragma("unroll") for (int k = 0; k < 2; ++k) dst[m][k] = *(const LAS bf16x8*)(lds + PG8_SA(b, h) + aoff + m * 2048 + k * 1024); } while (0)
; #define PG8_LDB(dst, b, h) do { _Pragma("unroll") for (int n = 0; n < 2; ++n) _Pragma("unroll") for (int k = 0; k < 2; ++k) dst[n][k] = *(const LAS bf16x8*)(lds + PG8_SB(b, h) + boff + n * 2048 + k * 1024); } while (0)
; #define PG8_MMA(ai, bj, At, Bt) do { __builtin_amdgcn_s_setprio(1); _Pragma("unroll") for (int m = 0; m < 4; ++m) _Pragma("unroll") for (int n = 0; n < 2; ++n) _Pragma("unroll") for (int k = 0; k < 2; ++k) \
;         acc[ai][bj][m][n] = __builtin_amdgcn_mfma_f32_16x16x32_bf16(Bt[n][k], At[m][k], acc[ai][bj][m][n], 0, 0, 0); __builtin_amdgcn_s_setprio(0); } while (0)
; #define PG8_WAIT_V(n) asm volatile("s_waitcnt vmcnt(" #n ")" ::: "memory")
; #define PG8_WAIT_L(n) asm volatile("s_waitcnt lgkmcnt(" #n ")" ::: "memory")
; #define PG8_BAR __builtin_amdgcn_s_barrier()
; #define PG8_SCHED __builtin_amdgcn_sched_barrier(0)
; template <class Epi>
; __device__ __forceinline__ void gemm_phase(LAS unsigned char* lds, const Gemm g, const StaticOrder& S, const Epi& E) {
;     ...
;             const bool last = (t == nt - 2);
;             const char* a1 = cA + (size_t)(t + 1) * kstep;
;             const char* a2 = last ? nA : cA + (size_t)(t + 2) * kstep; const char* b2 = last ? nB : cB + (size_t)(t + 2) * kstep;
;             const char* a3 = a2 + kstep; const char* b3 = b2 + kstep;
;             PG8_LDB(B0, 0, 0); PG8_LDB(B1, 0, 1); PG8_SCHED; PG8_LDA(At, 0, 0); PG8_STAGE(PG8_SA(1, 1), a1 + hstep, voffA);
;             PG8_WAIT_V(8); PG8_WAIT_L(0); PG8_BAR; PG8_MMA(0, 0, At, B0); PG8_MMA(0, 1, At, B1); PG8_BAR; PG8_SCHED;
;             PG8_LDA(At, 0, 1); PG8_STAGE(PG8_SB(0, 0), b2, voffB); PG8_STAGE(PG8_SB(0, 1), b2 + hstep, voffB); PG8_STAGE(PG8_SA(0, 0), a2, voffA);
.LBB0_1826:
	s_add_u32 s26, s24, 0xfff80080
	s_addc_u32 s27, s25, -1
	s_add_i32 s77, 0, 0x10000
	s_cmp_eq_u32 s76, 28
	s_cselect_b32 s29, s19, s27
	s_cselect_b32 s28, s45, s26
	s_cselect_b32 s27, s17, s75
	s_cselect_b32 s26, s55, s74
	s_add_i32 s80, 0, 0x14000
	v_add_u32_e32 v174, s77, v147
	v_add_u32_e32 v190, s80, v147
	ds_read_b128 v[158:161], v174
	ds_read_b128 v[166:169], v174 offset:1024
	ds_read_b128 v[170:173], v174 offset:2048
	ds_read_b128 v[174:177], v174 offset:3072
	ds_read_b128 v[178:181], v190
	ds_read_b128 v[182:185], v190 offset:1024
	ds_read_b128 v[186:189], v190 offset:2048
	ds_read_b128 v[190:193], v190 offset:3072
	v_lshl_add_u64 v[198:199], s[24:25], 0, v[140:141]
	s_add_i32 m0, s31, 0xc000
	ds_read_b128 v[212:215], v165
	ds_read_b128 v[216:219], v165 offset:1024
	ds_read_b128 v[220:223], v165 offset:2048
	ds_read_b128 v[224:227], v165 offset:3072
	ds_read_b128 v[228:231], v165 offset:4096
	ds_read_b128 v[232:235], v165 offset:5120
	ds_read_b128 v[236:239], v165 offset:6144
	ds_read_b128 v[240:243], v165 offset:7168
	global_load_lds_dwordx4 v[198:199], off
	v_lshl_add_u64 v[198:199], s[24:25], 0, v[156:157]
	s_add_i32 m0, s31, 0xe000
	s_nop 0
	global_load_lds_dwordx4 v[198:199], off
	s_waitcnt vmcnt(8)
	s_waitcnt lgkmcnt(0)
	s_setprio 1
	s_barrier
	v_mfma_f32_16x16x32_bf16 v[128:131], v[158:161], v[212:215], v[128:131]
	v_mfma_f32_16x16x32_bf16 v[124:127], v[170:173], v[212:215], v[124:127]
	v_mfma_f32_16x16x32_bf16 v[112:115], v[158:161], v[220:223], v[112:115]
	v_mfma_f32_16x16x32_bf16 v[108:111], v[170:173], v[220:223], v[108:111]
	v_mfma_f32_16x16x32_bf16 v[96:99], v[158:161], v[228:231], v[96:99]
	v_mfma_f32_16x16x32_bf16 v[92:95], v[170:173], v[228:231], v[92:95]
	v_mfma_f32_16x16x32_bf16 v[80:83], v[158:161], v[236:239], v[80:83]
	v_mfma_f32_16x16x32_bf16 v[76:79], v[170:173], v[236:239], v[76:79]
	v_mfma_f32_16x16x32_bf16 v[128:131], v[166:169], v[216:219], v[128:131]
	v_mfma_f32_16x16x32_bf16 v[124:127], v[174:177], v[216:219], v[124:127]
	v_mfma_f32_16x16x32_bf16 v[112:115], v[166:169], v[224:227], v[112:115]
	v_mfma_f32_16x16x32_bf16 v[108:111], v[174:177], v[224:227], v[108:111]
	v_mfma_f32_16x16x32_bf16 v[96:99], v[166:169], v[232:235], v[96:99]
	v_mfma_f32_16x16x32_bf16 v[92:95], v[174:177], v[232:235], v[92:95]
	v_mfma_f32_16x16x32_bf16 v[80:83], v[166:169], v[240:243], v[80:83]
	v_mfma_f32_16x16x32_bf16 v[76:79], v[174:177], v[240:243], v[76:79]
	v_mfma_f32_16x16x32_bf16 v[120:123], v[178:181], v[212:215], v[120:123]
	v_mfma_f32_16x16x32_bf16 v[116:119], v[186:189], v[212:215], v[116:119]
	v_mfma_f32_16x16x32_bf16 v[104:107], v[178:181], v[220:223], v[104:107]
	v_mfma_f32_16x16x32_bf16 v[100:103], v[186:189], v[220:223], v[100:103]
	v_mfma_f32_16x16x32_bf16 v[88:91], v[178:181], v[228:231], v[88:91]
	v_mfma_f32_16x16x32_bf16 v[84:87], v[186:189], v[228:231], v[84:87]
	v_mfma_f32_16x16x32_bf16 v[72:75], v[178:181], v[236:239], v[72:75]
	v_mfma_f32_16x16x32_bf16 v[68:71], v[186:189], v[236:239], v[68:71]
	v_mfma_f32_16x16x32_bf16 v[120:123], v[182:185], v[216:219], v[120:123]
	v_mfma_f32_16x16x32_bf16 v[116:119], v[190:193], v[216:219], v[116:119]
	v_mfma_f32_16x16x32_bf16 v[104:107], v[182:185], v[224:227], v[104:107]
	v_mfma_f32_16x16x32_bf16 v[100:103], v[190:193], v[224:227], v[100:103]
	v_mfma_f32_16x16x32_bf16 v[88:91], v[182:185], v[232:235], v[88:91]
	v_mfma_f32_16x16x32_bf16 v[84:87], v[190:193], v[232:235], v[84:87]
	v_mfma_f32_16x16x32_bf16 v[72:75], v[182:185], v[240:243], v[72:75]
	v_mfma_f32_16x16x32_bf16 v[68:71], v[190:193], v[240:243], v[68:71]
	s_barrier
	s_setprio 0
	s_add_i32 s77, s77, s30
	v_lshl_add_u64 v[198:199], s[26:27], 0, v[136:137]
	s_mov_b32 m0, s77
	ds_read_b128 v[212:215], v165 offset:16384
	ds_read_b128 v[216:219], v165 offset:17408
	ds_read_b128 v[220:223], v165 offset:18432
	ds_read_b128 v[224:227], v165 offset:19456
	ds_read_b128 v[228:231], v165 offset:20480
	ds_read_b128 v[232:235], v165 offset:21504
	ds_read_b128 v[236:239], v165 offset:22528
	ds_read_b128 v[240:243], v165 offset:23552
	global_load_lds_dwordx4 v[198:199], off
	s_add_i32 m0, s77, 0x2000
	s_add_u32 s78, s26, 0x80000
	v_lshl_add_u64 v[244:245], s[26:27], 0, v[132:133]
	s_addc_u32 s79, s27, 0
	s_add_i32 s77, s80, s30
	global_load_lds_dwordx4 v[244:245], off
	v_lshl_add_u64 v[246:247], s[78:79], 0, v[136:137]
	s_mov_b32 m0, s77
	v_lshl_add_u64 v[248:249], s[28:29], 0, v[134:135]
	global_load_lds_dwordx4 v[246:247], off
	v_lshl_add_u64 v[246:247], s[78:79], 0, v[132:133]
	s_add_i32 m0, s77, 0x2000
	s_nop 0
	global_load_lds_dwordx4 v[246:247], off
	v_lshl_add_u64 v[246:247], s[28:29], 0, v[138:139]
	s_mov_b32 m0, s31
	s_nop 0
	global_load_lds_dwordx4 v[246:247], off
	s_mov_b32 m0, s34
	s_nop 0
	global_load_lds_dwordx4 v[248:249], off
	s_waitcnt vmcnt(8)
	s_waitcnt lgkmcnt(0)
	s_setprio 1
	s_barrier
; #define PG8_STAGE(bufoff, gbase, voff) do { _Pragma("unroll") for (int _i = 0; _i < 2; ++_i) \
;         __builtin_amdgcn_global_load_lds((const unsigned*)((const char*)(gbase) + (voff)[_i]), (LAS unsigned*)(lds + (bufoff) + ldsw + _i * 8192), 16, 0, 0); } while (0)
; #define PG8_LDA(dst, b, h) do { _Pragma("unroll") for (int m = 0; m < 4; ++m) _Pragma("unroll") for (int k = 0; k < 2; ++k) dst[m][k] = *(const LAS bf16x8*)(lds + PG8_SA(b, h) + aoff + m * 2048 + k * 1024); } while (0)
; #define PG8_LDB(dst, b, h) do { _Pragma("unroll") for (int n = 0; n < 2; ++n) _Pragma("unroll") for (int k = 0; k < 2; ++k) dst[n][k] = *(const LAS bf16x8*)(lds + PG8_SB(b, h) + boff + n * 2048 + k * 1024); } while (0)
; #define PG8_MMA(ai, bj, At, Bt) do { __builtin_amdgcn_s_setprio(1); _Pragma("unroll") for (int m = 0; m < 4; ++m) _Pragma("unroll") for (int n = 0; n < 2; ++n) _Pragma("unroll") for (int k = 0; k < 2; ++k) \
;         acc[ai][bj][m][n] = __builtin_amdgcn_mfma_f32_16x16x32_bf16(Bt[n][k], At[m][k], acc[ai][bj][m][n], 0, 0, 0); __builtin_amdgcn_s_setprio(0); } while (0)
; #define PG8_WAIT_V(n) asm volatile("s_waitcnt vmcnt(" #n ")" ::: "memory")
; #define PG8_WAIT_L(n) asm volatile("s_waitcnt lgkmcnt(" #n ")" ::: "memory")
; #define PG8_BAR __builtin_amdgcn_s_barrier()
; #define PG8_SCHED __builtin_amdgcn_sched_barrier(0)
; template <class Epi>
; __device__ __forceinline__ void gemm_phase(LAS unsigned char* lds, const Gemm g, const StaticOrder& S, const Epi& E) {
;     ...
;             PG8_WAIT_V(8); PG8_WAIT_L(0); PG8_BAR; PG8_MMA(1, 0, At, B0); PG8_MMA(1, 1, At, B1); PG8_BAR; PG8_SCHED;
;             PG8_LDB(B0, 1, 0); PG8_LDB(B1, 1, 1); PG8_SCHED; PG8_LDA(At, 1, 0); PG8_STAGE(PG8_SA(0, 1), a2 + hstep, voffA);
;             PG8_WAIT_V(8); PG8_WAIT_L(0); PG8_BAR; PG8_MMA(0, 0, At, B0); PG8_MMA(0, 1, At, B1); PG8_BAR; PG8_SCHED;
	v_mfma_f32_16x16x32_bf16 v[64:67], v[158:161], v[212:215], v[64:67]
	v_mfma_f32_16x16x32_bf16 v[60:63], v[170:173], v[212:215], v[60:63]
	v_mfma_f32_16x16x32_bf16 v[56:59], v[158:161], v[220:223], v[56:59]
	v_mfma_f32_16x16x32_bf16 v[48:51], v[170:173], v[220:223], v[48:51]
	v_mfma_f32_16x16x32_bf16 v[40:43], v[158:161], v[228:231], v[40:43]
	v_mfma_f32_16x16x32_bf16 v[32:35], v[170:173], v[228:231], v[32:35]
	v_mfma_f32_16x16x32_bf16 v[20:23], v[158:161], v[236:239], v[20:23]
	v_mfma_f32_16x16x32_bf16 v[12:15], v[170:173], v[236:239], v[12:15]
	v_mfma_f32_16x16x32_bf16 v[64:67], v[166:169], v[216:219], v[64:67]
	v_mfma_f32_16x16x32_bf16 v[60:63], v[174:177], v[216:219], v[60:63]
	v_mfma_f32_16x16x32_bf16 v[56:59], v[166:169], v[224:227], v[56:59]
	v_mfma_f32_16x16x32_bf16 v[48:51], v[174:177], v[224:227], v[48:51]
	v_mfma_f32_16x16x32_bf16 v[40:43], v[166:169], v[232:235], v[40:43]
	v_mfma_f32_16x16x32_bf16 v[32:35], v[174:177], v[232:235], v[32:35]
	v_mfma_f32_16x16x32_bf16 v[20:23], v[166:169], v[240:243], v[20:23]
	v_mfma_f32_16x16x32_bf16 v[12:15], v[174:177], v[240:243], v[12:15]
	v_mfma_f32_16x16x32_bf16 v[52:55], v[178:181], v[212:215], v[52:55]
	v_mfma_f32_16x16x32_bf16 v[44:47], v[186:189], v[212:215], v[44:47]
	v_mfma_f32_16x16x32_bf16 v[36:39], v[178:181], v[220:223], v[36:39]
	v_mfma_f32_16x16x32_bf16 v[28:31], v[186:189], v[220:223], v[28:31]
	v_mfma_f32_16x16x32_bf16 v[24:27], v[178:181], v[228:231], v[24:27]
	v_mfma_f32_16x16x32_bf16 v[16:19], v[186:189], v[228:231], v[16:19]
	v_mfma_f32_16x16x32_bf16 v[8:11], v[178:181], v[236:239], v[8:11]
	v_mfma_f32_16x16x32_bf16 v[4:7], v[186:189], v[236:239], v[4:7]
	v_mfma_f32_16x16x32_bf16 v[52:55], v[182:185], v[216:219], v[52:55]
	v_mfma_f32_16x16x32_bf16 v[44:47], v[190:193], v[216:219], v[44:47]
	v_mfma_f32_16x16x32_bf16 v[36:39], v[182:185], v[224:227], v[36:39]
	v_mfma_f32_16x16x32_bf16 v[28:31], v[190:193], v[224:227], v[28:31]
	v_mfma_f32_16x16x32_bf16 v[24:27], v[182:185], v[232:235], v[24:27]
	v_mfma_f32_16x16x32_bf16 v[16:19], v[190:193], v[232:235], v[16:19]
	v_mfma_f32_16x16x32_bf16 v[8:11], v[182:185], v[240:243], v[8:11]
	v_mfma_f32_16x16x32_bf16 v[4:7], v[190:193], v[240:243], v[4:7]
	s_barrier
	s_setprio 0
	s_add_i32 s77, 0, 0x18000
	s_add_i32 s78, 0, 0x1c000
	v_add_u32_e32 v174, s77, v147
	v_add_u32_e32 v190, s78, v147
	ds_read_b128 v[158:161], v174
	ds_read_b128 v[166:169], v174 offset:1024
	ds_read_b128 v[170:173], v174 offset:2048
	ds_read_b128 v[174:177], v174 offset:3072
	ds_read_b128 v[178:181], v190
	ds_read_b128 v[182:185], v190 offset:1024
	ds_read_b128 v[186:189], v190 offset:2048
	ds_read_b128 v[190:193], v190 offset:3072
	s_add_u32 s28, s28, 0x80000
	s_addc_u32 s29, s29, 0
	s_mov_b32 m0, s35
	v_lshl_add_u64 v[250:251], s[28:29], 0, v[138:139]
	ds_read_b128 v[212:215], v165 offset:32768
	ds_read_b128 v[216:219], v165 offset:33792
	ds_read_b128 v[220:223], v165 offset:34816
	ds_read_b128 v[224:227], v165 offset:35840
	ds_read_b128 v[228:231], v165 offset:36864
	ds_read_b128 v[232:235], v165 offset:37888
	ds_read_b128 v[236:239], v165 offset:38912
	ds_read_b128 v[240:243], v165 offset:39936
	global_load_lds_dwordx4 v[250:251], off
	v_lshl_add_u64 v[250:251], s[28:29], 0, v[134:135]
	s_mov_b32 m0, s36
	s_nop 0
	global_load_lds_dwordx4 v[250:251], off
	s_waitcnt vmcnt(8)
	s_waitcnt lgkmcnt(0)
	s_setprio 1
	s_barrier
	v_mfma_f32_16x16x32_bf16 v[128:131], v[158:161], v[212:215], v[128:131]
	v_mfma_f32_16x16x32_bf16 v[124:127], v[170:173], v[212:215], v[124:127]
	v_mfma_f32_16x16x32_bf16 v[112:115], v[158:161], v[220:223], v[112:115]
	v_mfma_f32_16x16x32_bf16 v[108:111], v[170:173], v[220:223], v[108:111]
	v_mfma_f32_16x16x32_bf16 v[96:99], v[158:161], v[228:231], v[96:99]
	v_mfma_f32_16x16x32_bf16 v[92:95], v[170:173], v[228:231], v[92:95]
	v_mfma_f32_16x16x32_bf16 v[80:83], v[158:161], v[236:239], v[80:83]
	v_mfma_f32_16x16x32_bf16 v[76:79], v[170:173], v[236:239], v[76:79]
	v_mfma_f32_16x16x32_bf16 v[128:131], v[166:169], v[216:219], v[128:131]
	v_mfma_f32_16x16x32_bf16 v[124:127], v[174:177], v[216:219], v[124:127]
	v_mfma_f32_16x16x32_bf16 v[112:115], v[166:169], v[224:227], v[112:115]
	v_mfma_f32_16x16x32_bf16 v[108:111], v[174:177], v[224:227], v[108:111]
	v_mfma_f32_16x16x32_bf16 v[96:99], v[166:169], v[232:235], v[96:99]
	v_mfma_f32_16x16x32_bf16 v[92:95], v[174:177], v[232:235], v[92:95]
	v_mfma_f32_16x16x32_bf16 v[80:83], v[166:169], v[240:243], v[80:83]
	v_mfma_f32_16x16x32_bf16 v[76:79], v[174:177], v[240:243], v[76:79]
	v_mfma_f32_16x16x32_bf16 v[120:123], v[178:181], v[212:215], v[120:123]
	v_mfma_f32_16x16x32_bf16 v[116:119], v[186:189], v[212:215], v[116:119]
	v_mfma_f32_16x16x32_bf16 v[104:107], v[178:181], v[220:223], v[104:107]
	v_mfma_f32_16x16x32_bf16 v[100:103], v[186:189], v[220:223], v[100:103]
	v_mfma_f32_16x16x32_bf16 v[88:91], v[178:181], v[228:231], v[88:91]
	v_mfma_f32_16x16x32_bf16 v[84:87], v[186:189], v[228:231], v[84:87]
	v_mfma_f32_16x16x32_bf16 v[72:75], v[178:181], v[236:239], v[72:75]
	v_mfma_f32_16x16x32_bf16 v[68:71], v[186:189], v[236:239], v[68:71]
	v_mfma_f32_16x16x32_bf16 v[120:123], v[182:185], v[216:219], v[120:123]
	v_mfma_f32_16x16x32_bf16 v[116:119], v[190:193], v[216:219], v[116:119]
	v_mfma_f32_16x16x32_bf16 v[104:107], v[182:185], v[224:227], v[104:107]
	v_mfma_f32_16x16x32_bf16 v[100:103], v[190:193], v[224:227], v[100:103]
	v_mfma_f32_16x16x32_bf16 v[88:91], v[182:185], v[232:235], v[88:91]
	v_mfma_f32_16x16x32_bf16 v[84:87], v[190:193], v[232:235], v[84:87]
	v_mfma_f32_16x16x32_bf16 v[72:75], v[182:185], v[240:243], v[72:75]
	v_mfma_f32_16x16x32_bf16 v[68:71], v[190:193], v[240:243], v[68:71]
	s_barrier
; #define PG8_STAGE(bufoff, gbase, voff) do { _Pragma("unroll") for (int _i = 0; _i < 2; ++_i) \
;         __builtin_amdgcn_global_load_lds((const unsigned*)((const char*)(gbase) + (voff)[_i]), (LAS unsigned*)(lds + (bufoff) + ldsw + _i * 8192), 16, 0, 0); } while (0)
; #define PG8_LDA(dst, b, h) do { _Pragma("unroll") for (int m = 0; m < 4; ++m) _Pragma("unroll") for (int k = 0; k < 2; ++k) dst[m][k] = *(const LAS bf16x8*)(lds + PG8_SA(b, h) + aoff + m * 2048 + k * 1024); } while (0)
; #define PG8_MMA(ai, bj, At, Bt) do { __builtin_amdgcn_s_setprio(1); _Pragma("unroll") for (int m = 0; m < 4; ++m) _Pragma("unroll") for (int n = 0; n < 2; ++n) _Pragma("unroll") for (int k = 0; k < 2; ++k) \
;         acc[ai][bj][m][n] = __builtin_amdgcn_mfma_f32_16x16x32_bf16(Bt[n][k], At[m][k], acc[ai][bj][m][n], 0, 0, 0); __builtin_amdgcn_s_setprio(0); } while (0)
; #define PG8_WAIT_V(n) asm volatile("s_waitcnt vmcnt(" #n ")" ::: "memory")
; #define PG8_WAIT_L(n) asm volatile("s_waitcnt lgkmcnt(" #n ")" ::: "memory")
; #define PG8_BAR __builtin_amdgcn_s_barrier()
; #define PG8_SCHED __builtin_amdgcn_sched_barrier(0)
; template <class Epi>
; __device__ __forceinline__ void gemm_phase(LAS unsigned char* lds, const Gemm g, const StaticOrder& S, const Epi& E) {
;     ...
;             PG8_LDA(At, 1, 1); PG8_STAGE(PG8_SB(1, 0), b3, voffB); PG8_STAGE(PG8_SB(1, 1), b3 + hstep, voffB); PG8_STAGE(PG8_SA(1, 0), a3, voffA);
;             PG8_WAIT_V(8); PG8_WAIT_L(0); PG8_BAR; PG8_MMA(1, 0, At, B0); PG8_MMA(1, 1, At, B1); PG8_BAR; PG8_SCHED;
;         }
;         if (wr == 0) PG8_BAR;
	s_setprio 0
	s_add_i32 s28, s77, s30
	v_lshl_add_u64 v[198:199], v[198:199], 0, s[68:69]
	s_mov_b32 m0, s28
	ds_read_b128 v[212:215], v165 offset:49152
	ds_read_b128 v[216:219], v165 offset:50176
	ds_read_b128 v[220:223], v165 offset:51200
	ds_read_b128 v[224:227], v165 offset:52224
	ds_read_b128 v[228:231], v165 offset:53248
	ds_read_b128 v[232:235], v165 offset:54272
	ds_read_b128 v[236:239], v165 offset:55296
	ds_read_b128 v[240:243], v165 offset:56320
	global_load_lds_dwordx4 v[198:199], off
	s_add_i32 m0, s28, 0x2000
	s_add_u32 s26, s26, 0x80080
	v_lshl_add_u64 v[198:199], v[244:245], 0, s[68:69]
	s_addc_u32 s27, s27, 0
	s_add_i32 s28, s78, s30
	global_load_lds_dwordx4 v[198:199], off
	v_lshl_add_u64 v[198:199], s[26:27], 0, v[136:137]
	s_mov_b32 m0, s28
	s_nop 0
	global_load_lds_dwordx4 v[198:199], off
	v_lshl_add_u64 v[198:199], s[26:27], 0, v[132:133]
	s_add_i32 m0, s28, 0x2000
	s_nop 0
	global_load_lds_dwordx4 v[198:199], off
	v_lshl_add_u64 v[198:199], v[246:247], 0, s[68:69]
	s_mov_b32 m0, s37
	s_nop 0
	global_load_lds_dwordx4 v[198:199], off
	v_lshl_add_u64 v[198:199], v[248:249], 0, s[68:69]
	s_mov_b32 m0, s38
	s_nop 0
	global_load_lds_dwordx4 v[198:199], off
	s_waitcnt vmcnt(8)
	s_waitcnt lgkmcnt(0)
	s_setprio 1
	s_barrier
	v_mfma_f32_16x16x32_bf16 v[64:67], v[158:161], v[212:215], v[64:67]
	v_mfma_f32_16x16x32_bf16 v[60:63], v[170:173], v[212:215], v[60:63]
	v_mfma_f32_16x16x32_bf16 v[56:59], v[158:161], v[220:223], v[56:59]
	v_mfma_f32_16x16x32_bf16 v[48:51], v[170:173], v[220:223], v[48:51]
	v_mfma_f32_16x16x32_bf16 v[40:43], v[158:161], v[228:231], v[40:43]
	v_mfma_f32_16x16x32_bf16 v[32:35], v[170:173], v[228:231], v[32:35]
	v_mfma_f32_16x16x32_bf16 v[20:23], v[158:161], v[236:239], v[20:23]
	v_mfma_f32_16x16x32_bf16 v[12:15], v[170:173], v[236:239], v[12:15]
	v_mfma_f32_16x16x32_bf16 v[64:67], v[166:169], v[216:219], v[64:67]
	v_mfma_f32_16x16x32_bf16 v[60:63], v[174:177], v[216:219], v[60:63]
	v_mfma_f32_16x16x32_bf16 v[56:59], v[166:169], v[224:227], v[56:59]
	v_mfma_f32_16x16x32_bf16 v[48:51], v[174:177], v[224:227], v[48:51]
	v_mfma_f32_16x16x32_bf16 v[40:43], v[166:169], v[232:235], v[40:43]
	v_mfma_f32_16x16x32_bf16 v[32:35], v[174:177], v[232:235], v[32:35]
	v_mfma_f32_16x16x32_bf16 v[20:23], v[166:169], v[240:243], v[20:23]
	v_mfma_f32_16x16x32_bf16 v[12:15], v[174:177], v[240:243], v[12:15]
	v_mfma_f32_16x16x32_bf16 v[52:55], v[178:181], v[212:215], v[52:55]
	v_mfma_f32_16x16x32_bf16 v[44:47], v[186:189], v[212:215], v[44:47]
	v_mfma_f32_16x16x32_bf16 v[36:39], v[178:181], v[220:223], v[36:39]
	v_mfma_f32_16x16x32_bf16 v[28:31], v[186:189], v[220:223], v[28:31]
	v_mfma_f32_16x16x32_bf16 v[24:27], v[178:181], v[228:231], v[24:27]
	v_mfma_f32_16x16x32_bf16 v[16:19], v[186:189], v[228:231], v[16:19]
	v_mfma_f32_16x16x32_bf16 v[8:11], v[178:181], v[236:239], v[8:11]
	v_mfma_f32_16x16x32_bf16 v[4:7], v[186:189], v[236:239], v[4:7]
	v_mfma_f32_16x16x32_bf16 v[52:55], v[182:185], v[216:219], v[52:55]
	v_mfma_f32_16x16x32_bf16 v[44:47], v[190:193], v[216:219], v[44:47]
	v_mfma_f32_16x16x32_bf16 v[36:39], v[182:185], v[224:227], v[36:39]
	v_mfma_f32_16x16x32_bf16 v[28:31], v[190:193], v[224:227], v[28:31]
	v_mfma_f32_16x16x32_bf16 v[24:27], v[182:185], v[232:235], v[24:27]
	v_mfma_f32_16x16x32_bf16 v[16:19], v[190:193], v[232:235], v[16:19]
	v_mfma_f32_16x16x32_bf16 v[8:11], v[182:185], v[240:243], v[8:11]
	v_mfma_f32_16x16x32_bf16 v[4:7], v[190:193], v[240:243], v[4:7]
	s_barrier
	s_setprio 0
	s_add_i32 s76, s76, 2
	s_add_u32 s24, s24, 0x100
	s_addc_u32 s25, s25, 0
	s_add_u32 s74, s74, 0x100
	s_addc_u32 s75, s75, 0
	s_cmp_gt_u32 s76, 29
	s_cbranch_scc0 .LBB0_1826
	s_and_b64 vcc, exec, s[14:15]
	s_cbranch_vccz .LBB0_1829
	s_barrier

; #define PG8_STAGE(bufoff, gbase, voff) do { _Pragma("unroll") for (int _i = 0; _i < 2; ++_i) \
;         __builtin_amdgcn_global_load_lds((const unsigned*)((const char*)(gbase) + (voff)[_i]), (LAS unsigned*)(lds + (bufoff) + ldsw + _i * 8192), 16, 0, 0); } while (0)
; #define PG8_LDA(dst, b, h) do { _Pragma("unroll") for (int m = 0; m < 4; ++m) _Pragma("unroll") for (int k = 0; k < 2; ++k) dst[m][k] = *(const LAS bf16x8*)(lds + PG8_SA(b, h) + aoff + m * 2048 + k * 1024); } while (0)
; #define PG8_LDB(dst, b, h) do { _Pragma("unroll") for (int n = 0; n < 2; ++n) _Pragma("unroll") for (int k = 0; k < 2; ++k) dst[n][k] = *(const LAS bf16x8*)(lds + PG8_SB(b, h) + boff + n * 2048 + k * 1024); } while (0)
; #define PG8_MMA(ai, bj, At, Bt) do { __builtin_amdgcn_s_setprio(1); _Pragma("unroll") for (int m = 0; m < 4; ++m) _Pragma("unroll") for (int n = 0; n < 2; ++n) _Pragma("unroll") for (int k = 0; k < 2; ++k) \
;         acc[ai][bj][m][n] = __builtin_amdgcn_mfma_f32_16x16x32_bf16(Bt[n][k], At[m][k], acc[ai][bj][m][n], 0, 0, 0); __builtin_amdgcn_s_setprio(0); } while (0)
; #define PG8_WAIT_V(n) asm volatile("s_waitcnt vmcnt(" #n ")" ::: "memory")
; #define PG8_WAIT_L(n) asm volatile("s_waitcnt lgkmcnt(" #n ")" ::: "memory")
; #define PG8_BAR __builtin_amdgcn_s_barrier()
; #define PG8_SCHED __builtin_amdgcn_sched_barrier(0)
; template <class Epi>
; __device__ __forceinline__ void gemm_phase(LAS unsigned char* lds, const Gemm g, const StaticOrder& S, const Epi& E) {
;     ...
;             const bool last = (t == nt - 2);
;             const char* a1 = cA + (size_t)(t + 1) * kstep;
;             const char* a2 = last ? nA : cA + (size_t)(t + 2) * kstep; const char* b2 = last ? nB : cB + (size_t)(t + 2) * kstep;
;             const char* a3 = a2 + kstep; const char* b3 = b2 + kstep;
;             PG8_LDB(B0, 0, 0); PG8_LDB(B1, 0, 1); PG8_SCHED; PG8_LDA(At, 0, 0); PG8_STAGE(PG8_SA(1, 1), a1 + hstep, voffA);
;             PG8_WAIT_V(8); PG8_WAIT_L(0); PG8_BAR; PG8_MMA(0, 0, At, B0); PG8_MMA(0, 1, At, B1); PG8_BAR; PG8_SCHED;
;             PG8_LDA(At, 0, 1); PG8_STAGE(PG8_SB(0, 0), b2, voffB); PG8_STAGE(PG8_SB(0, 1), b2 + hstep, voffB); PG8_STAGE(PG8_SA(0, 0), a2, voffA);
.LBB0_1972:
	s_add_u32 s24, s22, 0xffe00080
	s_addc_u32 s25, s23, -1
	s_add_i32 s75, 0, 0x10000
	s_cmpk_eq_i32 s74, 0x7c
	s_cselect_b32 s27, s17, s25
	s_cselect_b32 s26, s45, s24
	v_add_u32_e32 v162, s75, v147
	s_cselect_b32 s25, s15, s61
	s_cselect_b32 s24, s55, s60
	s_add_i32 s78, 0, 0x14000
	ds_read_b128 v[158:161], v162
	ds_read_b128 v[166:169], v162 offset:1024
	ds_read_b128 v[170:173], v162 offset:2048
	ds_read_b128 v[174:177], v162 offset:3072
	v_add_u32_e32 v162, s78, v147
	ds_read_b128 v[178:181], v162
	ds_read_b128 v[182:185], v162 offset:1024
	ds_read_b128 v[186:189], v162 offset:2048
	ds_read_b128 v[190:193], v162 offset:3072
	v_lshl_add_u64 v[162:163], s[22:23], 0, v[140:141]
	s_add_i32 m0, s31, 0xc000
	ds_read_b128 v[212:215], v165
	ds_read_b128 v[216:219], v165 offset:1024
	ds_read_b128 v[220:223], v165 offset:2048
	ds_read_b128 v[224:227], v165 offset:3072
	ds_read_b128 v[228:231], v165 offset:4096
	ds_read_b128 v[232:235], v165 offset:5120
	ds_read_b128 v[236:239], v165 offset:6144
	ds_read_b128 v[240:243], v165 offset:7168
	global_load_lds_dwordx4 v[162:163], off
	v_lshl_add_u64 v[162:163], s[22:23], 0, v[156:157]
	s_add_i32 m0, s31, 0xe000
	s_nop 0
	global_load_lds_dwordx4 v[162:163], off
	s_waitcnt vmcnt(8)
	s_waitcnt lgkmcnt(0)
	s_setprio 1
	s_barrier
	v_mfma_f32_16x16x32_bf16 v[128:131], v[158:161], v[212:215], v[128:131]
	v_mfma_f32_16x16x32_bf16 v[124:127], v[170:173], v[212:215], v[124:127]
	v_mfma_f32_16x16x32_bf16 v[112:115], v[158:161], v[220:223], v[112:115]
	v_mfma_f32_16x16x32_bf16 v[108:111], v[170:173], v[220:223], v[108:111]
	v_mfma_f32_16x16x32_bf16 v[96:99], v[158:161], v[228:231], v[96:99]
	v_mfma_f32_16x16x32_bf16 v[92:95], v[170:173], v[228:231], v[92:95]
	v_mfma_f32_16x16x32_bf16 v[80:83], v[158:161], v[236:239], v[80:83]
	v_mfma_f32_16x16x32_bf16 v[76:79], v[170:173], v[236:239], v[76:79]
	v_mfma_f32_16x16x32_bf16 v[128:131], v[166:169], v[216:219], v[128:131]
	v_mfma_f32_16x16x32_bf16 v[124:127], v[174:177], v[216:219], v[124:127]
	v_mfma_f32_16x16x32_bf16 v[112:115], v[166:169], v[224:227], v[112:115]
	v_mfma_f32_16x16x32_bf16 v[108:111], v[174:177], v[224:227], v[108:111]
	v_mfma_f32_16x16x32_bf16 v[96:99], v[166:169], v[232:235], v[96:99]
	v_mfma_f32_16x16x32_bf16 v[92:95], v[174:177], v[232:235], v[92:95]
	v_mfma_f32_16x16x32_bf16 v[80:83], v[166:169], v[240:243], v[80:83]
	v_mfma_f32_16x16x32_bf16 v[76:79], v[174:177], v[240:243], v[76:79]
	v_mfma_f32_16x16x32_bf16 v[120:123], v[178:181], v[212:215], v[120:123]
	v_mfma_f32_16x16x32_bf16 v[116:119], v[186:189], v[212:215], v[116:119]
	v_mfma_f32_16x16x32_bf16 v[104:107], v[178:181], v[220:223], v[104:107]
	v_mfma_f32_16x16x32_bf16 v[100:103], v[186:189], v[220:223], v[100:103]
	v_mfma_f32_16x16x32_bf16 v[88:91], v[178:181], v[228:231], v[88:91]
	v_mfma_f32_16x16x32_bf16 v[84:87], v[186:189], v[228:231], v[84:87]
	v_mfma_f32_16x16x32_bf16 v[72:75], v[178:181], v[236:239], v[72:75]
	v_mfma_f32_16x16x32_bf16 v[68:71], v[186:189], v[236:239], v[68:71]
	v_mfma_f32_16x16x32_bf16 v[120:123], v[182:185], v[216:219], v[120:123]
	v_mfma_f32_16x16x32_bf16 v[116:119], v[190:193], v[216:219], v[116:119]
	v_mfma_f32_16x16x32_bf16 v[104:107], v[182:185], v[224:227], v[104:107]
	v_mfma_f32_16x16x32_bf16 v[100:103], v[190:193], v[224:227], v[100:103]
	v_mfma_f32_16x16x32_bf16 v[88:91], v[182:185], v[232:235], v[88:91]
	v_mfma_f32_16x16x32_bf16 v[84:87], v[190:193], v[232:235], v[84:87]
	v_mfma_f32_16x16x32_bf16 v[72:75], v[182:185], v[240:243], v[72:75]
	v_mfma_f32_16x16x32_bf16 v[68:71], v[190:193], v[240:243], v[68:71]
	s_barrier
	s_setprio 0
	s_add_i32 s75, s75, s30
	v_lshl_add_u64 v[162:163], s[24:25], 0, v[136:137]
	s_mov_b32 m0, s75
	ds_read_b128 v[212:215], v165 offset:16384
	ds_read_b128 v[216:219], v165 offset:17408
	ds_read_b128 v[220:223], v165 offset:18432
	ds_read_b128 v[224:227], v165 offset:19456
	ds_read_b128 v[228:231], v165 offset:20480
	ds_read_b128 v[232:235], v165 offset:21504
	ds_read_b128 v[236:239], v165 offset:22528
	ds_read_b128 v[240:243], v165 offset:23552
	global_load_lds_dwordx4 v[162:163], off
	s_add_i32 m0, s75, 0x2000
	s_add_u32 s76, s24, 0x200000
	v_lshl_add_u64 v[198:199], s[24:25], 0, v[132:133]
	s_addc_u32 s77, s25, 0
	s_add_i32 s75, s78, s30
	global_load_lds_dwordx4 v[198:199], off
	v_lshl_add_u64 v[244:245], s[76:77], 0, v[136:137]
	s_mov_b32 m0, s75
	v_lshl_add_u64 v[246:247], s[26:27], 0, v[134:135]
	global_load_lds_dwordx4 v[244:245], off
	v_lshl_add_u64 v[244:245], s[76:77], 0, v[132:133]
	s_add_i32 m0, s75, 0x2000
	s_nop 0
	global_load_lds_dwordx4 v[244:245], off
	v_lshl_add_u64 v[244:245], s[26:27], 0, v[138:139]
	s_mov_b32 m0, s31
	s_nop 0
	global_load_lds_dwordx4 v[244:245], off
	s_mov_b32 m0, s34
	s_nop 0
	global_load_lds_dwordx4 v[246:247], off
	s_waitcnt vmcnt(8)
	s_waitcnt lgkmcnt(0)
	s_setprio 1
	s_barrier
; #define PG8_STAGE(bufoff, gbase, voff) do { _Pragma("unroll") for (int _i = 0; _i < 2; ++_i) \
;         __builtin_amdgcn_global_load_lds((const unsigned*)((const char*)(gbase) + (voff)[_i]), (LAS unsigned*)(lds + (bufoff) + ldsw + _i * 8192), 16, 0, 0); } while (0)
; #define PG8_LDA(dst, b, h) do { _Pragma("unroll") for (int m = 0; m < 4; ++m) _Pragma("unroll") for (int k = 0; k < 2; ++k) dst[m][k] = *(const LAS bf16x8*)(lds + PG8_SA(b, h) + aoff + m * 2048 + k * 1024); } while (0)
; #define PG8_LDB(dst, b, h) do { _Pragma("unroll") for (int n = 0; n < 2; ++n) _Pragma("unroll") for (int k = 0; k < 2; ++k) dst[n][k] = *(const LAS bf16x8*)(lds + PG8_SB(b, h) + boff + n * 2048 + k * 1024); } while (0)
; #define PG8_MMA(ai, bj, At, Bt) do { __builtin_amdgcn_s_setprio(1); _Pragma("unroll") for (int m = 0; m < 4; ++m) _Pragma("unroll") for (int n = 0; n < 2; ++n) _Pragma("unroll") for (int k = 0; k < 2; ++k) \
;         acc[ai][bj][m][n] = __builtin_amdgcn_mfma_f32_16x16x32_bf16(Bt[n][k], At[m][k], acc[ai][bj][m][n], 0, 0, 0); __builtin_amdgcn_s_setprio(0); } while (0)
; #define PG8_WAIT_V(n) asm volatile("s_waitcnt vmcnt(" #n ")" ::: "memory")
; #define PG8_WAIT_L(n) asm volatile("s_waitcnt lgkmcnt(" #n ")" ::: "memory")
; #define PG8_BAR __builtin_amdgcn_s_barrier()
; #define PG8_SCHED __builtin_amdgcn_sched_barrier(0)
; template <class Epi>
; __device__ __forceinline__ void gemm_phase(LAS unsigned char* lds, const Gemm g, const StaticOrder& S, const Epi& E) {
;     ...
;             PG8_WAIT_V(8); PG8_WAIT_L(0); PG8_BAR; PG8_MMA(1, 0, At, B0); PG8_MMA(1, 1, At, B1); PG8_BAR; PG8_SCHED;
;             PG8_LDB(B0, 1, 0); PG8_LDB(B1, 1, 1); PG8_SCHED; PG8_LDA(At, 1, 0); PG8_STAGE(PG8_SA(0, 1), a2 + hstep, voffA);
;             PG8_WAIT_V(8); PG8_WAIT_L(0); PG8_BAR; PG8_MMA(0, 0, At, B0); PG8_MMA(0, 1, At, B1); PG8_BAR; PG8_SCHED;
	v_mfma_f32_16x16x32_bf16 v[64:67], v[158:161], v[212:215], v[64:67]
	v_mfma_f32_16x16x32_bf16 v[60:63], v[170:173], v[212:215], v[60:63]
	v_mfma_f32_16x16x32_bf16 v[48:51], v[158:161], v[220:223], v[48:51]
	v_mfma_f32_16x16x32_bf16 v[44:47], v[170:173], v[220:223], v[44:47]
	v_mfma_f32_16x16x32_bf16 v[32:35], v[158:161], v[228:231], v[32:35]
	v_mfma_f32_16x16x32_bf16 v[28:31], v[170:173], v[228:231], v[28:31]
	v_mfma_f32_16x16x32_bf16 v[16:19], v[158:161], v[236:239], v[16:19]
	v_mfma_f32_16x16x32_bf16 v[12:15], v[170:173], v[236:239], v[12:15]
	v_mfma_f32_16x16x32_bf16 v[64:67], v[166:169], v[216:219], v[64:67]
	v_mfma_f32_16x16x32_bf16 v[60:63], v[174:177], v[216:219], v[60:63]
	v_mfma_f32_16x16x32_bf16 v[48:51], v[166:169], v[224:227], v[48:51]
	v_mfma_f32_16x16x32_bf16 v[44:47], v[174:177], v[224:227], v[44:47]
	v_mfma_f32_16x16x32_bf16 v[32:35], v[166:169], v[232:235], v[32:35]
	v_mfma_f32_16x16x32_bf16 v[28:31], v[174:177], v[232:235], v[28:31]
	v_mfma_f32_16x16x32_bf16 v[16:19], v[166:169], v[240:243], v[16:19]
	v_mfma_f32_16x16x32_bf16 v[12:15], v[174:177], v[240:243], v[12:15]
	v_mfma_f32_16x16x32_bf16 v[56:59], v[178:181], v[212:215], v[56:59]
	v_mfma_f32_16x16x32_bf16 v[52:55], v[186:189], v[212:215], v[52:55]
	v_mfma_f32_16x16x32_bf16 v[40:43], v[178:181], v[220:223], v[40:43]
	v_mfma_f32_16x16x32_bf16 v[36:39], v[186:189], v[220:223], v[36:39]
	v_mfma_f32_16x16x32_bf16 v[24:27], v[178:181], v[228:231], v[24:27]
	v_mfma_f32_16x16x32_bf16 v[20:23], v[186:189], v[228:231], v[20:23]
	v_mfma_f32_16x16x32_bf16 v[8:11], v[178:181], v[236:239], v[8:11]
	v_mfma_f32_16x16x32_bf16 v[4:7], v[186:189], v[236:239], v[4:7]
	v_mfma_f32_16x16x32_bf16 v[56:59], v[182:185], v[216:219], v[56:59]
	v_mfma_f32_16x16x32_bf16 v[52:55], v[190:193], v[216:219], v[52:55]
	v_mfma_f32_16x16x32_bf16 v[40:43], v[182:185], v[224:227], v[40:43]
	v_mfma_f32_16x16x32_bf16 v[36:39], v[190:193], v[224:227], v[36:39]
	v_mfma_f32_16x16x32_bf16 v[24:27], v[182:185], v[232:235], v[24:27]
	v_mfma_f32_16x16x32_bf16 v[20:23], v[190:193], v[232:235], v[20:23]
	v_mfma_f32_16x16x32_bf16 v[8:11], v[182:185], v[240:243], v[8:11]
	v_mfma_f32_16x16x32_bf16 v[4:7], v[190:193], v[240:243], v[4:7]
	s_barrier
	s_setprio 0
	s_add_i32 s75, 0, 0x18000
	s_add_i32 s76, 0, 0x1c000
	v_add_u32_e32 v174, s75, v147
	v_add_u32_e32 v190, s76, v147
	ds_read_b128 v[158:161], v174
	ds_read_b128 v[166:169], v174 offset:1024
	ds_read_b128 v[170:173], v174 offset:2048
	ds_read_b128 v[174:177], v174 offset:3072
	ds_read_b128 v[178:181], v190
	ds_read_b128 v[182:185], v190 offset:1024
	ds_read_b128 v[186:189], v190 offset:2048
	ds_read_b128 v[190:193], v190 offset:3072
	s_add_u32 s26, s26, 0x200000
	s_addc_u32 s27, s27, 0
	s_mov_b32 m0, s35
	v_lshl_add_u64 v[248:249], s[26:27], 0, v[138:139]
	ds_read_b128 v[212:215], v165 offset:32768
	ds_read_b128 v[216:219], v165 offset:33792
	ds_read_b128 v[220:223], v165 offset:34816
	ds_read_b128 v[224:227], v165 offset:35840
	ds_read_b128 v[228:231], v165 offset:36864
	ds_read_b128 v[232:235], v165 offset:37888
	ds_read_b128 v[236:239], v165 offset:38912
	ds_read_b128 v[240:243], v165 offset:39936
	global_load_lds_dwordx4 v[248:249], off
	v_lshl_add_u64 v[248:249], s[26:27], 0, v[134:135]
	s_mov_b32 m0, s36
	s_nop 0
	global_load_lds_dwordx4 v[248:249], off
	s_waitcnt vmcnt(8)
	s_waitcnt lgkmcnt(0)
	s_setprio 1
	s_barrier
	v_mfma_f32_16x16x32_bf16 v[128:131], v[158:161], v[212:215], v[128:131]
	v_mfma_f32_16x16x32_bf16 v[124:127], v[170:173], v[212:215], v[124:127]
	v_mfma_f32_16x16x32_bf16 v[112:115], v[158:161], v[220:223], v[112:115]
	v_mfma_f32_16x16x32_bf16 v[108:111], v[170:173], v[220:223], v[108:111]
	v_mfma_f32_16x16x32_bf16 v[96:99], v[158:161], v[228:231], v[96:99]
	v_mfma_f32_16x16x32_bf16 v[92:95], v[170:173], v[228:231], v[92:95]
	v_mfma_f32_16x16x32_bf16 v[80:83], v[158:161], v[236:239], v[80:83]
	v_mfma_f32_16x16x32_bf16 v[76:79], v[170:173], v[236:239], v[76:79]
	v_mfma_f32_16x16x32_bf16 v[128:131], v[166:169], v[216:219], v[128:131]
	v_mfma_f32_16x16x32_bf16 v[124:127], v[174:177], v[216:219], v[124:127]
	v_mfma_f32_16x16x32_bf16 v[112:115], v[166:169], v[224:227], v[112:115]
	v_mfma_f32_16x16x32_bf16 v[108:111], v[174:177], v[224:227], v[108:111]
	v_mfma_f32_16x16x32_bf16 v[96:99], v[166:169], v[232:235], v[96:99]
	v_mfma_f32_16x16x32_bf16 v[92:95], v[174:177], v[232:235], v[92:95]
	v_mfma_f32_16x16x32_bf16 v[80:83], v[166:169], v[240:243], v[80:83]
	v_mfma_f32_16x16x32_bf16 v[76:79], v[174:177], v[240:243], v[76:79]
	v_mfma_f32_16x16x32_bf16 v[120:123], v[178:181], v[212:215], v[120:123]
	v_mfma_f32_16x16x32_bf16 v[116:119], v[186:189], v[212:215], v[116:119]
	v_mfma_f32_16x16x32_bf16 v[104:107], v[178:181], v[220:223], v[104:107]
	v_mfma_f32_16x16x32_bf16 v[100:103], v[186:189], v[220:223], v[100:103]
	v_mfma_f32_16x16x32_bf16 v[88:91], v[178:181], v[228:231], v[88:91]
	v_mfma_f32_16x16x32_bf16 v[84:87], v[186:189], v[228:231], v[84:87]
	v_mfma_f32_16x16x32_bf16 v[72:75], v[178:181], v[236:239], v[72:75]
	v_mfma_f32_16x16x32_bf16 v[68:71], v[186:189], v[236:239], v[68:71]
	v_mfma_f32_16x16x32_bf16 v[120:123], v[182:185], v[216:219], v[120:123]
	v_mfma_f32_16x16x32_bf16 v[116:119], v[190:193], v[216:219], v[116:119]
	v_mfma_f32_16x16x32_bf16 v[104:107], v[182:185], v[224:227], v[104:107]
	v_mfma_f32_16x16x32_bf16 v[100:103], v[190:193], v[224:227], v[100:103]
	v_mfma_f32_16x16x32_bf16 v[88:91], v[182:185], v[232:235], v[88:91]
	v_mfma_f32_16x16x32_bf16 v[84:87], v[190:193], v[232:235], v[84:87]
	v_mfma_f32_16x16x32_bf16 v[72:75], v[182:185], v[240:243], v[72:75]
	v_mfma_f32_16x16x32_bf16 v[68:71], v[190:193], v[240:243], v[68:71]
	s_barrier
; #define PG8_STAGE(bufoff, gbase, voff) do { _Pragma("unroll") for (int _i = 0; _i < 2; ++_i) \
;         __builtin_amdgcn_global_load_lds((const unsigned*)((const char*)(gbase) + (voff)[_i]), (LAS unsigned*)(lds + (bufoff) + ldsw + _i * 8192), 16, 0, 0); } while (0)
; #define PG8_LDA(dst, b, h) do { _Pragma("unroll") for (int m = 0; m < 4; ++m) _Pragma("unroll") for (int k = 0; k < 2; ++k) dst[m][k] = *(const LAS bf16x8*)(lds + PG8_SA(b, h) + aoff + m * 2048 + k * 1024); } while (0)
; #define PG8_MMA(ai, bj, At, Bt) do { __builtin_amdgcn_s_setprio(1); _Pragma("unroll") for (int m = 0; m < 4; ++m) _Pragma("unroll") for (int n = 0; n < 2; ++n) _Pragma("unroll") for (int k = 0; k < 2; ++k) \
;         acc[ai][bj][m][n] = __builtin_amdgcn_mfma_f32_16x16x32_bf16(Bt[n][k], At[m][k], acc[ai][bj][m][n], 0, 0, 0); __builtin_amdgcn_s_setprio(0); } while (0)
; #define PG8_WAIT_V(n) asm volatile("s_waitcnt vmcnt(" #n ")" ::: "memory")
; #define PG8_WAIT_L(n) asm volatile("s_waitcnt lgkmcnt(" #n ")" ::: "memory")
; #define PG8_BAR __builtin_amdgcn_s_barrier()
; #define PG8_SCHED __builtin_amdgcn_sched_barrier(0)
; template <class Epi>
; __device__ __forceinline__ void gemm_phase(LAS unsigned char* lds, const Gemm g, const StaticOrder& S, const Epi& E) {
;     ...
;             PG8_LDA(At, 1, 1); PG8_STAGE(PG8_SB(1, 0), b3, voffB); PG8_STAGE(PG8_SB(1, 1), b3 + hstep, voffB); PG8_STAGE(PG8_SA(1, 0), a3, voffA);
;             PG8_WAIT_V(8); PG8_WAIT_L(0); PG8_BAR; PG8_MMA(1, 0, At, B0); PG8_MMA(1, 1, At, B1); PG8_BAR; PG8_SCHED;
;         }
;         if (wr == 0) PG8_BAR;
	s_setprio 0
	s_add_i32 s26, s75, s30
	v_lshl_add_u64 v[162:163], v[162:163], 0, s[68:69]
	s_mov_b32 m0, s26
	ds_read_b128 v[212:215], v165 offset:49152
	ds_read_b128 v[216:219], v165 offset:50176
	ds_read_b128 v[220:223], v165 offset:51200
	ds_read_b128 v[224:227], v165 offset:52224
	ds_read_b128 v[228:231], v165 offset:53248
	ds_read_b128 v[232:235], v165 offset:54272
	ds_read_b128 v[236:239], v165 offset:55296
	ds_read_b128 v[240:243], v165 offset:56320
	global_load_lds_dwordx4 v[162:163], off
	s_add_i32 m0, s26, 0x2000
	s_add_u32 s24, s24, 0x200080
	v_lshl_add_u64 v[162:163], v[198:199], 0, s[68:69]
	s_addc_u32 s25, s25, 0
	s_add_i32 s26, s76, s30
	global_load_lds_dwordx4 v[162:163], off
	v_lshl_add_u64 v[162:163], s[24:25], 0, v[136:137]
	s_mov_b32 m0, s26
	s_nop 0
	global_load_lds_dwordx4 v[162:163], off
	v_lshl_add_u64 v[162:163], s[24:25], 0, v[132:133]
	s_add_i32 m0, s26, 0x2000
	s_nop 0
	global_load_lds_dwordx4 v[162:163], off
	v_lshl_add_u64 v[162:163], v[244:245], 0, s[68:69]
	s_mov_b32 m0, s38
	s_nop 0
	global_load_lds_dwordx4 v[162:163], off
	v_lshl_add_u64 v[162:163], v[246:247], 0, s[68:69]
	s_mov_b32 m0, s39
	s_nop 0
	global_load_lds_dwordx4 v[162:163], off
	s_waitcnt vmcnt(8)
	s_waitcnt lgkmcnt(0)
	s_setprio 1
	s_barrier
	v_mfma_f32_16x16x32_bf16 v[64:67], v[158:161], v[212:215], v[64:67]
	v_mfma_f32_16x16x32_bf16 v[60:63], v[170:173], v[212:215], v[60:63]
	v_mfma_f32_16x16x32_bf16 v[48:51], v[158:161], v[220:223], v[48:51]
	v_mfma_f32_16x16x32_bf16 v[44:47], v[170:173], v[220:223], v[44:47]
	v_mfma_f32_16x16x32_bf16 v[32:35], v[158:161], v[228:231], v[32:35]
	v_mfma_f32_16x16x32_bf16 v[28:31], v[170:173], v[228:231], v[28:31]
	v_mfma_f32_16x16x32_bf16 v[16:19], v[158:161], v[236:239], v[16:19]
	v_mfma_f32_16x16x32_bf16 v[12:15], v[170:173], v[236:239], v[12:15]
	v_mfma_f32_16x16x32_bf16 v[64:67], v[166:169], v[216:219], v[64:67]
	v_mfma_f32_16x16x32_bf16 v[60:63], v[174:177], v[216:219], v[60:63]
	v_mfma_f32_16x16x32_bf16 v[48:51], v[166:169], v[224:227], v[48:51]
	v_mfma_f32_16x16x32_bf16 v[44:47], v[174:177], v[224:227], v[44:47]
	v_mfma_f32_16x16x32_bf16 v[32:35], v[166:169], v[232:235], v[32:35]
	v_mfma_f32_16x16x32_bf16 v[28:31], v[174:177], v[232:235], v[28:31]
	v_mfma_f32_16x16x32_bf16 v[16:19], v[166:169], v[240:243], v[16:19]
	v_mfma_f32_16x16x32_bf16 v[12:15], v[174:177], v[240:243], v[12:15]
	v_mfma_f32_16x16x32_bf16 v[56:59], v[178:181], v[212:215], v[56:59]
	v_mfma_f32_16x16x32_bf16 v[52:55], v[186:189], v[212:215], v[52:55]
	v_mfma_f32_16x16x32_bf16 v[40:43], v[178:181], v[220:223], v[40:43]
	v_mfma_f32_16x16x32_bf16 v[36:39], v[186:189], v[220:223], v[36:39]
	v_mfma_f32_16x16x32_bf16 v[24:27], v[178:181], v[228:231], v[24:27]
	v_mfma_f32_16x16x32_bf16 v[20:23], v[186:189], v[228:231], v[20:23]
	v_mfma_f32_16x16x32_bf16 v[8:11], v[178:181], v[236:239], v[8:11]
	v_mfma_f32_16x16x32_bf16 v[4:7], v[186:189], v[236:239], v[4:7]
	v_mfma_f32_16x16x32_bf16 v[56:59], v[182:185], v[216:219], v[56:59]
	v_mfma_f32_16x16x32_bf16 v[52:55], v[190:193], v[216:219], v[52:55]
	v_mfma_f32_16x16x32_bf16 v[40:43], v[182:185], v[224:227], v[40:43]
	v_mfma_f32_16x16x32_bf16 v[36:39], v[190:193], v[224:227], v[36:39]
	v_mfma_f32_16x16x32_bf16 v[24:27], v[182:185], v[232:235], v[24:27]
	v_mfma_f32_16x16x32_bf16 v[20:23], v[190:193], v[232:235], v[20:23]
	v_mfma_f32_16x16x32_bf16 v[8:11], v[182:185], v[240:243], v[8:11]
	v_mfma_f32_16x16x32_bf16 v[4:7], v[190:193], v[240:243], v[4:7]
	s_barrier
	s_setprio 0
	s_add_i32 s74, s74, 2
	s_add_u32 s22, s22, 0x100
	s_addc_u32 s23, s23, 0
	s_add_u32 s60, s60, 0x100
	s_addc_u32 s61, s61, 0
	s_cmpk_gt_u32 s74, 0x7d
	s_cbranch_scc0 .LBB0_1972
	s_and_b64 vcc, exec, s[12:13]
	s_cbranch_vccz .LBB0_1975
	s_barrier
